# DeltaNet task: chunkwise WY form on f32 matrix cores (32-step chunks, state in LDS, one triangular substitution per chunk), replaces the per-step recurrence loop and pair dots
# speedup vs baseline: 1.0106x; 1.0100x over previous
; __device__ __forceinline__ int otid() { int t = threadIdx.x; asm volatile("" : "+v"(t)); return t; }
; __device__ __forceinline__ void dn_task(const Params& p, int l, int task, char* smem) {
;   const int tid = otid();
;   const int dir = task & 1, hd = (task >> 1) & 3, vh = (task >> 3) & 1, b = task >> 4;
;   float* qs = (float*)smem;
;   float* ks = qs + 32 * 68;
;   float* vs = ks + 32 * 68;
;   float* al = vs + 32 * 64;
;   float* dots = al + 64;
;   float* wl = al + 128;
;   bf16_t* rawb = (bf16_t*)(wl + 5 * 192);
;   const bf16_t* P = WS_BF(p, OFF_P);
;   const float* cw = p.in[11] + (size_t)l * 5 * 768;
;   const float Aexp = __expf(p.in[12][l * 8 + dir * 4 + hd]);
;   const float dtb = p.in[13][l * 8 + dir * 4 + hd];
;   bf16_t* O = WS_BF(p, OFF_SC) + (size_t)dir * NTOK * 256;
;   const int v = vh * 32 + (tid >> 3), kq = tid & 7;
;   for (int i = tid; i < 5 * 192; i += 256) {
;     const int j = i / 192, c = i - j * 192;
;     wl[i] = cw[j * 768 + (c >> 6) * 256 + hd * 64 + (c & 63)];
;   }
;   float ra = 0.f, rb = 0.f;
;   f32x2 S2[4];
; #pragma unroll
;   for (int i = 0; i < 4; ++i) S2[i] = mk2(0.f, 0.f);
.LBB0_191:
	s_or_b64 exec, exec, s[52:53]
	v_mul_f32_e32 v0, 0x3fb8aa3b, v6
	v_and_b32_e32 v19, 3, v138
	v_exp_f32_e32 v162, v0
	v_ashrrev_i32_e32 v0, 2, v138
	v_lshlrev_b32_e32 v6, 6, v19
	s_movk_i32 s36, 0x110
	v_ashrrev_i32_e32 v18, 3, v18
	s_mul_i32 s98, s54, 0x1200000
	v_mad_u64_u32 v[142:143], s[54:55], v0, s36, v[6:7]
	v_add_u32_e32 v18, v18, v7
	v_lshlrev_b32_e32 v164, 4, v19
	v_cmp_eq_u32_e64 s[54:55], 0, v19
	v_mul_lo_u32 v19, v18, 48
	s_lshl_b32 s52, s60, 2
	v_sub_u32_e32 v19, v138, v19
	s_and_b32 s68, s52, 32
	v_ashrrev_i32_e32 v163, 3, v138
	v_and_b32_e32 v3, 7, v138
	v_cmp_gt_i32_e32 vcc, 32, v0
	v_ashrrev_i32_e32 v23, 4, v19
	v_lshl_add_u64 v[20:21], v[104:105], 0, s[98:99]
	s_lshl_b32 s86, s57, 11
	v_cndmask_b32_e32 v143, 1.0, v188, vcc
	v_and_b32_e32 v165, 3, v0
	v_lshlrev_b32_e32 v0, 3, v3
	v_lshlrev_b32_e32 v166, 5, v3
	v_cmp_eq_u32_e64 s[56:57], 0, v3
	s_lshl_b32 s69, s68, 2
	v_cmp_eq_u32_e32 vcc, 2, v23
	v_lshl_add_u64 v[144:145], v[4:5], 1, v[94:95]
	v_lshlrev_b32_e32 v4, 8, v163
	v_lshlrev_b32_e32 v3, 4, v3
	s_lshl_b32 s98, s61, 1
	v_add_lshl_u32 v167, v163, s68, 2
	v_cndmask_b32_e64 v25, v189, 64, vcc
	v_or3_b32 v198, s69, v4, v3
	v_lshl_add_u64 v[4:5], v[20:21], 0, s[98:99]
	s_lshl_b32 s68, s68, 1
	s_mov_b32 s69, s99
	v_cmp_eq_u32_e32 vcc, 1, v23
	v_lshlrev_b32_e32 v169, 3, v18
	v_lshl_add_u64 v[4:5], v[4:5], 0, s[68:69]
	s_movk_i32 s61, 0xc00
	v_cndmask_b32_e32 v23, v190, v191, vcc
	v_cmp_lt_u32_e32 vcc, 15, v19
	v_lshlrev_b32_e32 v168, 4, v19
	v_lshlrev_b32_e32 v24, 3, v19
	v_lshl_add_u64 v[146:147], v[4:5], 0, v[0:1]
	v_mul_lo_u32 v18, v18, s61
	v_or_b32_e32 v0, 1, v169
	s_movk_i32 s61, 0x180
	v_cndmask_b32_e32 v19, 0, v23, vcc
	v_sub_u32_e32 v23, 31, v169
	v_mul_lo_u32 v20, v0, s61
	s_movk_i32 s61, 0xf0
	v_cndmask_b32_e64 v23, v23, v169, s[40:41]
	v_and_or_b32 v19, v168, s61, v19
	v_mul_lo_u32 v23, v23, v25
	v_lshl_add_u32 v199, v23, 2, v19
	v_sub_u32_e32 v23, 31, v0
	v_cndmask_b32_e64 v0, v23, v0, s[40:41]
	v_or_b32_e32 v3, 2, v169
	v_mul_lo_u32 v0, v0, v25
	v_lshl_add_u32 v200, v0, 2, v19
	v_sub_u32_e32 v0, 31, v3
	v_cndmask_b32_e64 v0, v0, v3, s[40:41]
	v_or_b32_e32 v4, 3, v169
	v_mul_lo_u32 v0, v0, v25
	v_lshl_add_u32 v201, v0, 2, v19
	v_sub_u32_e32 v0, 31, v4
	v_cndmask_b32_e64 v0, v0, v4, s[40:41]
	v_or_b32_e32 v5, 4, v169
	v_mul_lo_u32 v0, v0, v25
	v_lshl_add_u32 v202, v0, 2, v19
	v_sub_u32_e32 v0, 31, v5
	v_cndmask_b32_e64 v0, v0, v5, s[40:41]
	v_or_b32_e32 v21, 5, v169
	v_mul_lo_u32 v0, v0, v25
	v_lshl_add_u32 v203, v0, 2, v19
	v_sub_u32_e32 v0, 31, v21
	v_cndmask_b32_e64 v0, v0, v21, s[40:41]
	v_or_b32_e32 v28, 6, v169
	v_mul_lo_u32 v0, v0, v25
	v_lshl_add_u32 v204, v0, 2, v19
	v_sub_u32_e32 v0, 31, v28
	v_cndmask_b32_e64 v0, v0, v28, s[40:41]
	v_or_b32_e32 v29, 7, v169
	v_mul_lo_u32 v0, v0, v25
	v_lshl_add_u32 v205, v0, 2, v19
	v_sub_u32_e32 v0, 31, v29
	v_cndmask_b32_e64 v0, v0, v29, s[40:41]
	v_mul_lo_u32 v0, v0, v25
	v_add_u32_e32 v207, v8, v7
	v_lshl_add_u32 v206, v0, 2, v19
	v_mul_lo_u32 v0, v207, s37
	v_add_lshl_u32 v0, v0, v138, 5
	v_and_b32_e32 v4, 0xffffff00, v0
	v_ashrrev_i32_e32 v5, 31, v4
	v_add_u32_e32 v208, v11, v10
	v_lshl_add_u64 v[4:5], v[4:5], 1, v[94:95]
	v_mul_lo_u32 v0, v208, s37
	v_lshl_add_u64 v[4:5], v[4:5], 0, s[98:99]
	v_mov_b32_e32 v3, v1
	v_add_lshl_u32 v0, v0, v9, 5
	v_lshl_add_u64 v[148:149], v[4:5], 0, v[2:3]
	v_and_b32_e32 v4, 0xffffff00, v0
	v_ashrrev_i32_e32 v5, 31, v4
	v_add_u32_e32 v209, v14, v13
	v_lshl_add_u64 v[4:5], v[4:5], 1, v[94:95]
	v_mul_lo_u32 v0, v209, s37
	v_lshl_add_u64 v[4:5], v[4:5], 0, s[98:99]
	v_add_lshl_u32 v0, v0, v12, 5
	v_lshl_add_u64 v[150:151], v[4:5], 0, v[2:3]
	v_and_b32_e32 v4, 0xffffff00, v0
	v_ashrrev_i32_e32 v5, 31, v4
	v_add_u32_e32 v210, v17, v16
	v_lshl_add_u64 v[4:5], v[4:5], 1, v[94:95]
	v_mul_lo_u32 v0, v210, s37
	v_ashrrev_i32_e32 v22, 4, v138
	s_movk_i32 s70, 0x220
	v_lshl_add_u64 v[4:5], v[4:5], 0, s[98:99]
	v_add_lshl_u32 v0, v0, v15, 5
	v_mul_lo_u32 v170, v22, s70
	s_movk_i32 s70, 0x88
	v_lshl_add_u64 v[152:153], v[4:5], 0, v[2:3]
	v_and_b32_e32 v4, 0xffffff00, v0
	v_mul_lo_u32 v22, v22, s70
	v_ashrrev_i32_e32 v5, 31, v4
	v_add_u32_e32 v27, 0x44, v22
	v_lshl_add_u64 v[4:5], v[4:5], 1, v[94:95]
	v_cmp_eq_u32_e32 vcc, 3, v165
	s_lshl_b32 s60, s60, 4
	v_lshl_add_u64 v[4:5], v[4:5], 0, s[98:99]
	v_cndmask_b32_e32 v0, v22, v27, vcc
	s_and_b32 s60, s60, 0x80
	s_waitcnt vmcnt(0)
	v_lshlrev_b32_e32 v8, 4, v138
	v_lshlrev_b32_e32 v9, 4, v9
	v_lshl_add_u64 v[154:155], v[4:5], 0, v[2:3]
	v_lshl_add_u32 v211, v0, 2, v6
	v_lshl_add_u32 v0, v163, 2, s60
	v_mov_b32_e32 v2, v1
	v_mov_b32_e32 v4, v1
	v_mov_b32_e32 v5, v1
	v_mov_b32_e32 v6, v1
	v_mov_b32_e32 v7, v1
	s_movk_i32 s52, 0xc0
	v_sub_u32_e32 v24, v168, v24
	v_lshlrev_b32_e32 v26, 2, v138
	v_lshlrev_b32_e32 v10, 4, v12
	v_lshlrev_b32_e32 v11, 4, v15
	v_add_u32_e32 v212, 0x4400, v0
	v_mov_b32_e32 v0, v1
	v_add_u32_e32 v216, 0x7500, v8
	v_add_u32_e32 v217, 0x7500, v9
	v_mov_b64_e32 v[8:9], v[6:7]
	v_cmp_gt_i32_e64 s[52:53], s52, v138
	s_mov_b32 s81, 0
	v_add_u32_e32 v171, 0x2310, v170
	v_add_u32_e32 v196, 0x110, v170
	v_and_b32_e32 v197, -4, v138
	v_add_u32_e32 v213, 0x220, v166
	v_add_u32_e32 v214, v24, v18
	v_add_u32_e32 v215, v24, v20
	v_add_u32_e32 v218, 0x7500, v10
	v_add_u32_e32 v219, 0x7500, v11
	v_add_u32_e32 v220, 0x6000, v26
	v_mov_b64_e32 v[6:7], v[4:5]
	v_mov_b64_e32 v[4:5], v[2:3]
	v_mov_b64_e32 v[2:3], v[0:1]
	v_lshlrev_b32_e32 v0, 4, v172
	v_add_u32_e32 v0, 0x11600, v0
	ds_write_b128 v0, v[2:5]
	ds_write_b128 v0, v[2:5] offset:4096
	v_add_u32_e32 v0, 0x2000, v0
	v_min_u32_e32 v0, 0x136f0, v0
	ds_write_b128 v0, v[2:5]
	s_waitcnt vmcnt(0) lgkmcnt(0)
	s_barrier
	s_branch .LBB0_193

; __device__ __forceinline__ void dn_task(const Params& p, int l, int task, char* smem) {
;     ...
;     {
;       const int did = tid >> 2, pp = did >> 2, wh = did & 3, part = tid & 3;
;       const float* xr = (wh == 0) ? (ks + (2 * pp + 1) * 68) : (wh == 1) ? (qs + (2 * pp) * 68) : (qs + (2 * pp + 1) * 68);
;       const float* yr = (wh == 3) ? (ks + (2 * pp + 1) * 68) : (ks + (2 * pp) * 68);
;       float sdot = 0.f;
; #pragma unroll
;       for (int i = 0; i < 16; ++i) sdot += xr[part * 16 + i] * yr[part * 16 + i];
;       sdot = quad_sum(sdot);
;       if (part == 0) dots[did] = sdot;
;     }
.LBB0_207:
	v_and_b32_e32 v221, 63, v172
	v_and_b32_e32 v222, 15, v221
	v_lshrrev_b32_e32 v223, 4, v221
	v_mul_u32_u24_e32 v224, 0x110, v222
	v_lshl_add_u32 v224, v223, 6, v224
	v_mul_u32_u24_e32 v225, 0x240, v223
	v_lshl_add_u32 v225, v222, 2, v225
	v_readfirstlane_b32 s60, v172
	s_nop 3
	s_lshr_b32 s60, s60, 6
	v_lshrrev_b32_e32 v244, 3, v172
	v_lshlrev_b32_e32 v244, 2, v244
	v_sub_u32_e32 v248, v167, v244
	s_and_b32 s61, s60, 1
	s_lshl_b32 s61, s61, 6
	v_mul_u32_u24_e32 v244, 0x840, v223
	v_lshl_add_u32 v244, v222, 2, v244
	s_add_i32 s61, s61, 0x11600
	v_add_u32_e32 v244, s61, v244
	ds_read_b32 v10, v244 offset:0
	ds_read_b32 v11, v244 offset:132
	ds_read_b32 v12, v244 offset:264
	ds_read_b32 v13, v244 offset:396
	ds_read_b32 v14, v244 offset:528
	ds_read_b32 v15, v244 offset:660
	ds_read_b32 v16, v244 offset:792
	ds_read_b32 v17, v244 offset:924
	ds_read_b32 v18, v244 offset:1056
	ds_read_b32 v19, v244 offset:1188
	ds_read_b32 v20, v244 offset:1320
	ds_read_b32 v21, v244 offset:1452
	ds_read_b32 v22, v244 offset:1584
	ds_read_b32 v23, v244 offset:1716
	ds_read_b32 v24, v244 offset:1848
	ds_read_b32 v25, v244 offset:1980
	s_lshr_b32 s61, s60, 1
	s_mul_i32 s70, s61, 0x1100
	v_add_u32_e32 v246, s70, v224
	ds_read_b128 v[66:69], v246 offset:8704
	ds_read_b128 v[70:73], v246 offset:8720
	ds_read_b128 v[74:77], v246 offset:8736
	ds_read_b128 v[78:81], v246 offset:8752
	s_cmp_eq_u32 s60, 3
	s_cbranch_scc1 .Ldc_w3
	s_cmp_ge_u32 s60, 1
	s_cselect_b32 s61, 0x1100, 0
	s_cmp_eq_u32 s60, 2
	s_cselect_b32 s70, 0x1100, 0
	v_add_u32_e32 v244, s61, v224
	v_add_u32_e32 v245, s70, v224
	ds_read_b128 v[26:29], v244 offset:8704
	ds_read_b128 v[30:33], v244 offset:8720
	ds_read_b128 v[34:37], v244 offset:8736
	ds_read_b128 v[38:41], v244 offset:8752
	ds_read_b128 v[42:45], v245 offset:8704
	ds_read_b128 v[46:49], v245 offset:8720
	ds_read_b128 v[50:53], v245 offset:8736
	ds_read_b128 v[54:57], v245 offset:8752
	s_waitcnt lgkmcnt(0)
	v_mfma_f32_16x16x4_f32 v[62:65], v66, v10, 0
	v_mfma_f32_16x16x4_f32 v[58:61], v26, v42, 0
	v_mfma_f32_16x16x4_f32 v[62:65], v67, v11, v[62:65]
	v_mfma_f32_16x16x4_f32 v[58:61], v27, v43, v[58:61]
	v_mfma_f32_16x16x4_f32 v[62:65], v68, v12, v[62:65]
	v_mfma_f32_16x16x4_f32 v[58:61], v28, v44, v[58:61]
	v_mfma_f32_16x16x4_f32 v[62:65], v69, v13, v[62:65]
	v_mfma_f32_16x16x4_f32 v[58:61], v29, v45, v[58:61]
	v_mfma_f32_16x16x4_f32 v[62:65], v70, v14, v[62:65]
	v_mfma_f32_16x16x4_f32 v[58:61], v30, v46, v[58:61]
	v_mfma_f32_16x16x4_f32 v[62:65], v71, v15, v[62:65]
	v_mfma_f32_16x16x4_f32 v[58:61], v31, v47, v[58:61]
	v_mfma_f32_16x16x4_f32 v[62:65], v72, v16, v[62:65]
	v_mfma_f32_16x16x4_f32 v[58:61], v32, v48, v[58:61]
	v_mfma_f32_16x16x4_f32 v[62:65], v73, v17, v[62:65]
	v_mfma_f32_16x16x4_f32 v[58:61], v33, v49, v[58:61]
	v_mfma_f32_16x16x4_f32 v[62:65], v74, v18, v[62:65]
	v_mfma_f32_16x16x4_f32 v[58:61], v34, v50, v[58:61]
	v_mfma_f32_16x16x4_f32 v[62:65], v75, v19, v[62:65]
	v_mfma_f32_16x16x4_f32 v[58:61], v35, v51, v[58:61]
	v_mfma_f32_16x16x4_f32 v[62:65], v76, v20, v[62:65]
	v_mfma_f32_16x16x4_f32 v[58:61], v36, v52, v[58:61]
	v_mfma_f32_16x16x4_f32 v[62:65], v77, v21, v[62:65]
	v_mfma_f32_16x16x4_f32 v[58:61], v37, v53, v[58:61]
	v_mfma_f32_16x16x4_f32 v[62:65], v78, v22, v[62:65]
	v_mfma_f32_16x16x4_f32 v[58:61], v38, v54, v[58:61]
	v_mfma_f32_16x16x4_f32 v[62:65], v79, v23, v[62:65]
	v_mfma_f32_16x16x4_f32 v[58:61], v39, v55, v[58:61]
	v_mfma_f32_16x16x4_f32 v[62:65], v80, v24, v[62:65]
	v_mfma_f32_16x16x4_f32 v[58:61], v40, v56, v[58:61]
	v_mfma_f32_16x16x4_f32 v[62:65], v81, v25, v[62:65]
	v_mfma_f32_16x16x4_f32 v[58:61], v41, v57, v[58:61]
	s_branch .Ldc_b1
.Ldc_w3:
	s_waitcnt lgkmcnt(0)
	v_mfma_f32_16x16x4_f32 v[62:65], v66, v10, 0
	v_mfma_f32_16x16x4_f32 v[62:65], v67, v11, v[62:65]
	v_mfma_f32_16x16x4_f32 v[62:65], v68, v12, v[62:65]
	v_mfma_f32_16x16x4_f32 v[62:65], v69, v13, v[62:65]
	v_mfma_f32_16x16x4_f32 v[62:65], v70, v14, v[62:65]
	v_mfma_f32_16x16x4_f32 v[62:65], v71, v15, v[62:65]
	v_mfma_f32_16x16x4_f32 v[62:65], v72, v16, v[62:65]
	v_mfma_f32_16x16x4_f32 v[62:65], v73, v17, v[62:65]
	v_mfma_f32_16x16x4_f32 v[62:65], v74, v18, v[62:65]
	v_mfma_f32_16x16x4_f32 v[62:65], v75, v19, v[62:65]
	v_mfma_f32_16x16x4_f32 v[62:65], v76, v20, v[62:65]
	v_mfma_f32_16x16x4_f32 v[62:65], v77, v21, v[62:65]
	v_mfma_f32_16x16x4_f32 v[62:65], v78, v22, v[62:65]
	v_mfma_f32_16x16x4_f32 v[62:65], v79, v23, v[62:65]
	v_mfma_f32_16x16x4_f32 v[62:65], v80, v24, v[62:65]
	v_mfma_f32_16x16x4_f32 v[62:65], v81, v25, v[62:65]
	ds_read_b128 v[10:13], v1 offset:25600
	ds_read_b128 v[14:17], v1 offset:25616
	ds_read_b128 v[18:21], v1 offset:25632
	ds_read_b128 v[22:25], v1 offset:25648
	ds_read_b128 v[26:29], v1 offset:25664
	ds_read_b128 v[30:33], v1 offset:25680
	ds_read_b128 v[34:37], v1 offset:25696
	ds_read_b128 v[38:41], v1 offset:25712
	v_and_b32_e32 v45, 31, v221
	v_mul_u32_u24_e32 v46, 0x90, v45
	v_mov_b32_e32 v47, v45
	v_lshlrev_b32_e32 v45, 2, v45
	v_mov_b32_e32 v42, 1.0
	v_lshrrev_b32_e32 v48, 2, v221
	v_mul_u32_u24_e32 v48, 0x90, v48
	v_and_b32_e32 v49, 3, v221
	v_lshl_add_u32 v48, v49, 4, v48
	v_mov_b32_e32 v50, 0
	v_mov_b32_e32 v51, 0
	v_mov_b32_e32 v52, 0
	v_mov_b32_e32 v53, 0
	ds_write_b128 v48, v[50:53] offset:48704
	s_waitcnt lgkmcnt(0)
	v_cmp_ge_u32_e32 vcc, 0, v47
	v_cndmask_b32_e32 v44, 0, v42, vcc
	ds_write_b32 v45, v44 offset:53248
	v_mul_f32_e32 v43, v42, v11
	v_cndmask_b32_e32 v42, v42, v43, vcc
	v_cmp_ge_u32_e32 vcc, 1, v47
	v_cndmask_b32_e32 v44, 0, v42, vcc
	ds_write_b32 v45, v44 offset:53392
	v_mul_f32_e32 v43, v42, v12
	v_cndmask_b32_e32 v42, v42, v43, vcc
	v_cmp_ge_u32_e32 vcc, 2, v47
	v_cndmask_b32_e32 v44, 0, v42, vcc
	ds_write_b32 v45, v44 offset:53536
	v_mul_f32_e32 v43, v42, v13
	v_cndmask_b32_e32 v42, v42, v43, vcc
	v_cmp_ge_u32_e32 vcc, 3, v47
	v_cndmask_b32_e32 v44, 0, v42, vcc
	ds_write_b32 v45, v44 offset:53680
	v_mul_f32_e32 v43, v42, v14
	v_cndmask_b32_e32 v42, v42, v43, vcc
	v_cmp_ge_u32_e32 vcc, 4, v47
	v_cndmask_b32_e32 v44, 0, v42, vcc
	ds_write_b32 v45, v44 offset:53824
	v_mul_f32_e32 v43, v42, v15
	v_cndmask_b32_e32 v42, v42, v43, vcc
	v_cmp_ge_u32_e32 vcc, 5, v47
	v_cndmask_b32_e32 v44, 0, v42, vcc
	ds_write_b32 v45, v44 offset:53968
	v_mul_f32_e32 v43, v42, v16
	v_cndmask_b32_e32 v42, v42, v43, vcc
	v_cmp_ge_u32_e32 vcc, 6, v47
	v_cndmask_b32_e32 v44, 0, v42, vcc
	ds_write_b32 v45, v44 offset:54112
	v_mul_f32_e32 v43, v42, v17
	v_cndmask_b32_e32 v42, v42, v43, vcc
	v_cmp_ge_u32_e32 vcc, 7, v47
	v_cndmask_b32_e32 v44, 0, v42, vcc
	ds_write_b32 v45, v44 offset:54256
	v_mul_f32_e32 v43, v42, v18
	v_cndmask_b32_e32 v42, v42, v43, vcc
	v_cmp_ge_u32_e32 vcc, 8, v47
	v_cndmask_b32_e32 v44, 0, v42, vcc
	ds_write_b32 v45, v44 offset:54400
	v_mul_f32_e32 v43, v42, v19
	v_cndmask_b32_e32 v42, v42, v43, vcc
	v_cmp_ge_u32_e32 vcc, 9, v47
	v_cndmask_b32_e32 v44, 0, v42, vcc
	ds_write_b32 v45, v44 offset:54544
	v_mul_f32_e32 v43, v42, v20
	v_cndmask_b32_e32 v42, v42, v43, vcc
	v_cmp_ge_u32_e32 vcc, 10, v47
	v_cndmask_b32_e32 v44, 0, v42, vcc
	ds_write_b32 v45, v44 offset:54688
	v_mul_f32_e32 v43, v42, v21
	v_cndmask_b32_e32 v42, v42, v43, vcc
	v_cmp_ge_u32_e32 vcc, 11, v47
	v_cndmask_b32_e32 v44, 0, v42, vcc
	ds_write_b32 v45, v44 offset:54832
	v_mul_f32_e32 v43, v42, v22
	v_cndmask_b32_e32 v42, v42, v43, vcc
	v_cmp_ge_u32_e32 vcc, 12, v47
	v_cndmask_b32_e32 v44, 0, v42, vcc
	ds_write_b32 v45, v44 offset:54976
	v_mul_f32_e32 v43, v42, v23
	v_cndmask_b32_e32 v42, v42, v43, vcc
	v_cmp_ge_u32_e32 vcc, 13, v47
	v_cndmask_b32_e32 v44, 0, v42, vcc
	ds_write_b32 v45, v44 offset:55120
	v_mul_f32_e32 v43, v42, v24
	v_cndmask_b32_e32 v42, v42, v43, vcc
	v_cmp_ge_u32_e32 vcc, 14, v47
	v_cndmask_b32_e32 v44, 0, v42, vcc
	ds_write_b32 v45, v44 offset:55264
	v_mul_f32_e32 v43, v42, v25
	v_cndmask_b32_e32 v42, v42, v43, vcc
	v_cmp_ge_u32_e32 vcc, 15, v47
	v_cndmask_b32_e32 v44, 0, v42, vcc
	ds_write_b32 v45, v44 offset:55408
	v_mul_f32_e32 v43, v42, v26
	v_cndmask_b32_e32 v42, v42, v43, vcc
	v_cmp_ge_u32_e32 vcc, 16, v47
	v_cndmask_b32_e32 v44, 0, v42, vcc
	ds_write_b32 v45, v44 offset:55552
	v_mul_f32_e32 v43, v42, v27
	v_cndmask_b32_e32 v42, v42, v43, vcc
	v_cmp_ge_u32_e32 vcc, 17, v47
	v_cndmask_b32_e32 v44, 0, v42, vcc
	ds_write_b32 v45, v44 offset:55696
	v_mul_f32_e32 v43, v42, v28
	v_cndmask_b32_e32 v42, v42, v43, vcc
	v_cmp_ge_u32_e32 vcc, 18, v47
	v_cndmask_b32_e32 v44, 0, v42, vcc
	ds_write_b32 v45, v44 offset:55840
	v_mul_f32_e32 v43, v42, v29
	v_cndmask_b32_e32 v42, v42, v43, vcc
	v_cmp_ge_u32_e32 vcc, 19, v47
	v_cndmask_b32_e32 v44, 0, v42, vcc
	ds_write_b32 v45, v44 offset:55984
	v_mul_f32_e32 v43, v42, v30
	v_cndmask_b32_e32 v42, v42, v43, vcc
	v_cmp_ge_u32_e32 vcc, 20, v47
	v_cndmask_b32_e32 v44, 0, v42, vcc
	ds_write_b32 v45, v44 offset:56128
	v_mul_f32_e32 v43, v42, v31
	v_cndmask_b32_e32 v42, v42, v43, vcc
	v_cmp_ge_u32_e32 vcc, 21, v47
	v_cndmask_b32_e32 v44, 0, v42, vcc
	ds_write_b32 v45, v44 offset:56272
	v_mul_f32_e32 v43, v42, v32
	v_cndmask_b32_e32 v42, v42, v43, vcc
	v_cmp_ge_u32_e32 vcc, 22, v47
	v_cndmask_b32_e32 v44, 0, v42, vcc
	ds_write_b32 v45, v44 offset:56416
	v_mul_f32_e32 v43, v42, v33
	v_cndmask_b32_e32 v42, v42, v43, vcc
	v_cmp_ge_u32_e32 vcc, 23, v47
	v_cndmask_b32_e32 v44, 0, v42, vcc
	ds_write_b32 v45, v44 offset:56560
	v_mul_f32_e32 v43, v42, v34
	v_cndmask_b32_e32 v42, v42, v43, vcc
	v_cmp_ge_u32_e32 vcc, 24, v47
	v_cndmask_b32_e32 v44, 0, v42, vcc
	ds_write_b32 v45, v44 offset:56704
	v_mul_f32_e32 v43, v42, v35
	v_cndmask_b32_e32 v42, v42, v43, vcc
	v_cmp_ge_u32_e32 vcc, 25, v47
	v_cndmask_b32_e32 v44, 0, v42, vcc
	ds_write_b32 v45, v44 offset:56848
	v_mul_f32_e32 v43, v42, v36
	v_cndmask_b32_e32 v42, v42, v43, vcc
	v_cmp_ge_u32_e32 vcc, 26, v47
	v_cndmask_b32_e32 v44, 0, v42, vcc
	ds_write_b32 v45, v44 offset:56992
	v_mul_f32_e32 v43, v42, v37
	v_cndmask_b32_e32 v42, v42, v43, vcc
	v_cmp_ge_u32_e32 vcc, 27, v47
	v_cndmask_b32_e32 v44, 0, v42, vcc
	ds_write_b32 v45, v44 offset:57136
	v_mul_f32_e32 v43, v42, v38
	v_cndmask_b32_e32 v42, v42, v43, vcc
	v_cmp_ge_u32_e32 vcc, 28, v47
	v_cndmask_b32_e32 v44, 0, v42, vcc
	ds_write_b32 v45, v44 offset:57280
	v_mul_f32_e32 v43, v42, v39
	v_cndmask_b32_e32 v42, v42, v43, vcc
	v_cmp_ge_u32_e32 vcc, 29, v47
	v_cndmask_b32_e32 v44, 0, v42, vcc
	ds_write_b32 v45, v44 offset:57424
	v_mul_f32_e32 v43, v42, v40
	v_cndmask_b32_e32 v42, v42, v43, vcc
	v_cmp_ge_u32_e32 vcc, 30, v47
	v_cndmask_b32_e32 v44, 0, v42, vcc
	ds_write_b32 v45, v44 offset:57568
	v_mul_f32_e32 v43, v42, v41
	v_cndmask_b32_e32 v42, v42, v43, vcc
	v_cmp_ge_u32_e32 vcc, 31, v47
	v_cndmask_b32_e32 v44, 0, v42, vcc
	ds_write_b32 v45, v44 offset:57712
	s_waitcnt lgkmcnt(0)
	ds_read_b32 v44, v46 offset:53248
	ds_read_b32 v43, v45 offset:57712
	s_waitcnt lgkmcnt(0)
	v_mul_f32_e32 v44, v10, v44
	v_add_u32_e32 v49, 0x13700, v45
	ds_write_b32 v49, v44
	ds_write_b32 v49, v43 offset:128
.Ldc_b1:
	s_waitcnt lgkmcnt(0)
	s_barrier
	s_lshr_b32 s61, s60, 1
	s_and_b32 s70, s60, 1
	s_lshl_b32 s70, s70, 6
	s_lshl_b32 s71, s61, 12
	s_add_i32 s71, s71, s70
	v_lshl_add_u32 v244, v223, 10, v248
	v_lshl_add_u32 v244, v222, 2, v244
	v_add_u32_e32 v244, s71, v244
	s_lshl_b32 s71, s61, 6
	v_lshl_add_u32 v245, v223, 4, s71
	v_add_u32_e32 v135, 0x13700, v245
	s_mul_i32 s71, s61, 0x900
	s_add_i32 s71, s71, s70
	v_add_u32_e32 v246, s71, v225
	ds_read_b128 v[70:73], v245 offset:25728
	ds_read_b128 v[74:77], v135
	ds_read_b32 v66, v244 offset:17408
	ds_read_b32 v67, v244 offset:17664
	ds_read_b32 v68, v244 offset:17920
	ds_read_b32 v69, v244 offset:18176
	s_waitcnt lgkmcnt(0)
	v_mul_f32_e32 v78, v74, v62
	v_sub_f32_e32 v78, v66, v78
	v_mul_f32_e32 v78, v70, v78
	ds_write_b32 v246, v78 offset:57856
	v_mul_f32_e32 v79, v75, v63
	v_sub_f32_e32 v79, v67, v79
	v_mul_f32_e32 v79, v71, v79
	ds_write_b32 v246, v79 offset:58000
	v_mul_f32_e32 v80, v76, v64
	v_sub_f32_e32 v80, v68, v80
	v_mul_f32_e32 v80, v72, v80
	ds_write_b32 v246, v80 offset:58144
	v_mul_f32_e32 v81, v77, v65
	v_sub_f32_e32 v81, v69, v81
	v_mul_f32_e32 v81, v73, v81
	ds_write_b32 v246, v81 offset:58288
	s_cmp_eq_u32 s60, 3
	s_cbranch_scc1 .Ldc_b2
	s_cmp_ge_u32 s60, 1
	s_cselect_b32 s61, 0x900, 0
	s_cselect_b32 s83, 64, 0
	s_cmp_eq_u32 s60, 2
	s_cselect_b32 s70, 64, 0
	s_cselect_b32 s84, 0x900, 0
	s_add_i32 s71, s61, s70
	v_add_u32_e32 v244, s71, v225
	v_lshl_add_u32 v245, v223, 4, s83
	v_mul_u32_u24_e32 v246, 0x90, v222
	v_lshl_add_u32 v246, v223, 4, v246
	s_add_i32 s71, s84, s83
	v_add_u32_e32 v246, s71, v246
	ds_read_b32 v66, v244 offset:53248
	ds_read_b32 v67, v244 offset:53392
	ds_read_b32 v68, v244 offset:53536
	ds_read_b32 v69, v244 offset:53680
	ds_read_b128 v[70:73], v245 offset:25728
	s_waitcnt lgkmcnt(0)
	v_mul_f32_e32 v74, v58, v66
	v_mul_f32_e64 v74, -v70, v74
	v_mul_f32_e32 v75, v59, v67
	v_mul_f32_e64 v75, -v71, v75
	v_mul_f32_e32 v76, v60, v68
	v_mul_f32_e64 v76, -v72, v76
	v_mul_f32_e32 v77, v61, v69
	v_mul_f32_e64 v77, -v73, v77
	ds_write_b128 v246, v[74:77] offset:44032
.Ldc_b2:
	s_waitcnt lgkmcnt(0)
	s_barrier
	s_cmp_ge_u32 s60, 2
	s_cbranch_scc1 .Ldc_s2q
	s_cmp_eq_u32 s60, 1
	s_cbranch_scc1 .Ldc_s2k
	v_and_b32_e32 v135, 31, v221
	v_lshlrev_b32_e32 v135, 2, v135
	ds_read_b32 v10, v135 offset:57856
	ds_read_b32 v11, v135 offset:58000
	ds_read_b32 v12, v135 offset:58144
	ds_read_b32 v13, v135 offset:58288
	ds_read_b32 v14, v135 offset:58432
	ds_read_b32 v15, v135 offset:58576
	ds_read_b32 v16, v135 offset:58720
	ds_read_b32 v17, v135 offset:58864
	ds_read_b32 v18, v135 offset:59008
	ds_read_b32 v19, v135 offset:59152
	ds_read_b32 v20, v135 offset:59296
	ds_read_b32 v21, v135 offset:59440
	ds_read_b32 v22, v135 offset:59584
	ds_read_b32 v23, v135 offset:59728
	ds_read_b32 v24, v135 offset:59872
	ds_read_b32 v25, v135 offset:60016
	ds_read_b32 v26, v135 offset:60160
	ds_read_b32 v27, v135 offset:60304
	ds_read_b32 v28, v135 offset:60448
	ds_read_b32 v29, v135 offset:60592
	ds_read_b32 v30, v135 offset:60736
	ds_read_b32 v31, v135 offset:60880
	ds_read_b32 v32, v135 offset:61024
	ds_read_b32 v33, v135 offset:61168
	ds_read_b32 v34, v135 offset:61312
	ds_read_b32 v35, v135 offset:61456
	ds_read_b32 v36, v135 offset:61600
	ds_read_b32 v37, v135 offset:61744
	ds_read_b32 v38, v135 offset:61888
	ds_read_b32 v39, v135 offset:62032
	ds_read_b32 v40, v135 offset:62176
	ds_read_b32 v41, v135 offset:62320
	ds_read_b128 v[42:45], v1 offset:44032
	ds_read_b128 v[46:49], v1 offset:44048
	ds_read_b128 v[50:53], v1 offset:44064
	ds_read_b128 v[54:57], v1 offset:44080
	ds_read_b128 v[58:61], v1 offset:44096
	ds_read_b128 v[62:65], v1 offset:44112
	ds_read_b128 v[66:69], v1 offset:44128
	ds_read_b128 v[70:73], v1 offset:44144
	ds_read_b128 v[74:77], v1 offset:44176
	ds_read_b128 v[78:81], v1 offset:44192
	ds_read_b128 v[82:85], v1 offset:44208
	ds_read_b128 v[86:89], v1 offset:44224
	ds_read_b128 v[226:229], v1 offset:44240
	ds_read_b128 v[230:233], v1 offset:44256
	ds_read_b128 v[234:237], v1 offset:44272
	ds_read_b128 v[238:241], v1 offset:44288
	s_waitcnt lgkmcnt(8)
	v_fmac_f32_e32 v11, v43, v10
	v_pk_fma_f32 v[12:13], v[44:45], v[10:11], v[12:13] op_sel:[0,0,0] op_sel_hi:[1,0,1]
	v_pk_fma_f32 v[14:15], v[46:47], v[10:11], v[14:15] op_sel:[0,0,0] op_sel_hi:[1,0,1]
	v_pk_fma_f32 v[16:17], v[48:49], v[10:11], v[16:17] op_sel:[0,0,0] op_sel_hi:[1,0,1]
	v_pk_fma_f32 v[18:19], v[50:51], v[10:11], v[18:19] op_sel:[0,0,0] op_sel_hi:[1,0,1]
	v_pk_fma_f32 v[20:21], v[52:53], v[10:11], v[20:21] op_sel:[0,0,0] op_sel_hi:[1,0,1]
	v_pk_fma_f32 v[22:23], v[54:55], v[10:11], v[22:23] op_sel:[0,0,0] op_sel_hi:[1,0,1]
	v_pk_fma_f32 v[24:25], v[56:57], v[10:11], v[24:25] op_sel:[0,0,0] op_sel_hi:[1,0,1]
	v_pk_fma_f32 v[26:27], v[58:59], v[10:11], v[26:27] op_sel:[0,0,0] op_sel_hi:[1,0,1]
	v_pk_fma_f32 v[28:29], v[60:61], v[10:11], v[28:29] op_sel:[0,0,0] op_sel_hi:[1,0,1]
	v_pk_fma_f32 v[30:31], v[62:63], v[10:11], v[30:31] op_sel:[0,0,0] op_sel_hi:[1,0,1]
	v_pk_fma_f32 v[32:33], v[64:65], v[10:11], v[32:33] op_sel:[0,0,0] op_sel_hi:[1,0,1]
	v_pk_fma_f32 v[34:35], v[66:67], v[10:11], v[34:35] op_sel:[0,0,0] op_sel_hi:[1,0,1]
	v_pk_fma_f32 v[36:37], v[68:69], v[10:11], v[36:37] op_sel:[0,0,0] op_sel_hi:[1,0,1]
	v_pk_fma_f32 v[38:39], v[70:71], v[10:11], v[38:39] op_sel:[0,0,0] op_sel_hi:[1,0,1]
	v_pk_fma_f32 v[40:41], v[72:73], v[10:11], v[40:41] op_sel:[0,0,0] op_sel_hi:[1,0,1]
	ds_read_b128 v[42:45], v1 offset:44320
	ds_read_b128 v[46:49], v1 offset:44336
	ds_read_b128 v[50:53], v1 offset:44352
	ds_read_b128 v[54:57], v1 offset:44368
	ds_read_b128 v[58:61], v1 offset:44384
	ds_read_b128 v[62:65], v1 offset:44400
	ds_read_b128 v[66:69], v1 offset:44416
	ds_read_b128 v[70:73], v1 offset:44432
	s_waitcnt lgkmcnt(8)
	v_pk_fma_f32 v[12:13], v[76:77], v[10:11], v[12:13] op_sel:[0,1,0] op_sel_hi:[1,1,1]
	v_pk_fma_f32 v[14:15], v[78:79], v[10:11], v[14:15] op_sel:[0,1,0] op_sel_hi:[1,1,1]
	v_pk_fma_f32 v[16:17], v[80:81], v[10:11], v[16:17] op_sel:[0,1,0] op_sel_hi:[1,1,1]
	v_pk_fma_f32 v[18:19], v[82:83], v[10:11], v[18:19] op_sel:[0,1,0] op_sel_hi:[1,1,1]
	v_pk_fma_f32 v[20:21], v[84:85], v[10:11], v[20:21] op_sel:[0,1,0] op_sel_hi:[1,1,1]
	v_pk_fma_f32 v[22:23], v[86:87], v[10:11], v[22:23] op_sel:[0,1,0] op_sel_hi:[1,1,1]
	v_pk_fma_f32 v[24:25], v[88:89], v[10:11], v[24:25] op_sel:[0,1,0] op_sel_hi:[1,1,1]
	v_pk_fma_f32 v[26:27], v[226:227], v[10:11], v[26:27] op_sel:[0,1,0] op_sel_hi:[1,1,1]
	v_pk_fma_f32 v[28:29], v[228:229], v[10:11], v[28:29] op_sel:[0,1,0] op_sel_hi:[1,1,1]
	v_pk_fma_f32 v[30:31], v[230:231], v[10:11], v[30:31] op_sel:[0,1,0] op_sel_hi:[1,1,1]
	v_pk_fma_f32 v[32:33], v[232:233], v[10:11], v[32:33] op_sel:[0,1,0] op_sel_hi:[1,1,1]
	v_pk_fma_f32 v[34:35], v[234:235], v[10:11], v[34:35] op_sel:[0,1,0] op_sel_hi:[1,1,1]
	v_pk_fma_f32 v[36:37], v[236:237], v[10:11], v[36:37] op_sel:[0,1,0] op_sel_hi:[1,1,1]
	v_pk_fma_f32 v[38:39], v[238:239], v[10:11], v[38:39] op_sel:[0,1,0] op_sel_hi:[1,1,1]
	v_pk_fma_f32 v[40:41], v[240:241], v[10:11], v[40:41] op_sel:[0,1,0] op_sel_hi:[1,1,1]
	ds_read_b128 v[78:81], v1 offset:44480
	ds_read_b128 v[82:85], v1 offset:44496
	ds_read_b128 v[86:89], v1 offset:44512
	ds_read_b128 v[226:229], v1 offset:44528
	ds_read_b128 v[230:233], v1 offset:44544
	ds_read_b128 v[234:237], v1 offset:44560
	ds_read_b128 v[238:241], v1 offset:44576
	s_waitcnt lgkmcnt(7)
	v_fmac_f32_e32 v13, v45, v12
	v_pk_fma_f32 v[14:15], v[46:47], v[12:13], v[14:15] op_sel:[0,0,0] op_sel_hi:[1,0,1]
	v_pk_fma_f32 v[16:17], v[48:49], v[12:13], v[16:17] op_sel:[0,0,0] op_sel_hi:[1,0,1]
	v_pk_fma_f32 v[18:19], v[50:51], v[12:13], v[18:19] op_sel:[0,0,0] op_sel_hi:[1,0,1]
	v_pk_fma_f32 v[20:21], v[52:53], v[12:13], v[20:21] op_sel:[0,0,0] op_sel_hi:[1,0,1]
	v_pk_fma_f32 v[22:23], v[54:55], v[12:13], v[22:23] op_sel:[0,0,0] op_sel_hi:[1,0,1]
	v_pk_fma_f32 v[24:25], v[56:57], v[12:13], v[24:25] op_sel:[0,0,0] op_sel_hi:[1,0,1]
	v_pk_fma_f32 v[26:27], v[58:59], v[12:13], v[26:27] op_sel:[0,0,0] op_sel_hi:[1,0,1]
	v_pk_fma_f32 v[28:29], v[60:61], v[12:13], v[28:29] op_sel:[0,0,0] op_sel_hi:[1,0,1]
	v_pk_fma_f32 v[30:31], v[62:63], v[12:13], v[30:31] op_sel:[0,0,0] op_sel_hi:[1,0,1]
	v_pk_fma_f32 v[32:33], v[64:65], v[12:13], v[32:33] op_sel:[0,0,0] op_sel_hi:[1,0,1]
	v_pk_fma_f32 v[34:35], v[66:67], v[12:13], v[34:35] op_sel:[0,0,0] op_sel_hi:[1,0,1]
	v_pk_fma_f32 v[36:37], v[68:69], v[12:13], v[36:37] op_sel:[0,0,0] op_sel_hi:[1,0,1]
	v_pk_fma_f32 v[38:39], v[70:71], v[12:13], v[38:39] op_sel:[0,0,0] op_sel_hi:[1,0,1]
	v_pk_fma_f32 v[40:41], v[72:73], v[12:13], v[40:41] op_sel:[0,0,0] op_sel_hi:[1,0,1]
	ds_read_b128 v[46:49], v1 offset:44624
	ds_read_b128 v[50:53], v1 offset:44640
	ds_read_b128 v[54:57], v1 offset:44656
	ds_read_b128 v[58:61], v1 offset:44672
	ds_read_b128 v[62:65], v1 offset:44688
	ds_read_b128 v[66:69], v1 offset:44704
	ds_read_b128 v[70:73], v1 offset:44720
	s_waitcnt lgkmcnt(7)
	v_pk_fma_f32 v[14:15], v[78:79], v[12:13], v[14:15] op_sel:[0,1,0] op_sel_hi:[1,1,1]
	v_pk_fma_f32 v[16:17], v[80:81], v[12:13], v[16:17] op_sel:[0,1,0] op_sel_hi:[1,1,1]
	v_pk_fma_f32 v[18:19], v[82:83], v[12:13], v[18:19] op_sel:[0,1,0] op_sel_hi:[1,1,1]
	v_pk_fma_f32 v[20:21], v[84:85], v[12:13], v[20:21] op_sel:[0,1,0] op_sel_hi:[1,1,1]
	v_pk_fma_f32 v[22:23], v[86:87], v[12:13], v[22:23] op_sel:[0,1,0] op_sel_hi:[1,1,1]
	v_pk_fma_f32 v[24:25], v[88:89], v[12:13], v[24:25] op_sel:[0,1,0] op_sel_hi:[1,1,1]
	v_pk_fma_f32 v[26:27], v[226:227], v[12:13], v[26:27] op_sel:[0,1,0] op_sel_hi:[1,1,1]
	v_pk_fma_f32 v[28:29], v[228:229], v[12:13], v[28:29] op_sel:[0,1,0] op_sel_hi:[1,1,1]
	v_pk_fma_f32 v[30:31], v[230:231], v[12:13], v[30:31] op_sel:[0,1,0] op_sel_hi:[1,1,1]
	v_pk_fma_f32 v[32:33], v[232:233], v[12:13], v[32:33] op_sel:[0,1,0] op_sel_hi:[1,1,1]
	v_pk_fma_f32 v[34:35], v[234:235], v[12:13], v[34:35] op_sel:[0,1,0] op_sel_hi:[1,1,1]
	v_pk_fma_f32 v[36:37], v[236:237], v[12:13], v[36:37] op_sel:[0,1,0] op_sel_hi:[1,1,1]
	v_pk_fma_f32 v[38:39], v[238:239], v[12:13], v[38:39] op_sel:[0,1,0] op_sel_hi:[1,1,1]
	v_pk_fma_f32 v[40:41], v[240:241], v[12:13], v[40:41] op_sel:[0,1,0] op_sel_hi:[1,1,1]
	ds_read_b128 v[78:81], v1 offset:44768
	ds_read_b128 v[82:85], v1 offset:44784
	ds_read_b128 v[86:89], v1 offset:44800
	ds_read_b128 v[226:229], v1 offset:44816
	ds_read_b128 v[230:233], v1 offset:44832
	ds_read_b128 v[234:237], v1 offset:44848
	ds_read_b128 v[238:241], v1 offset:44864
	s_waitcnt lgkmcnt(7)
	v_fmac_f32_e32 v15, v47, v14
	v_pk_fma_f32 v[16:17], v[48:49], v[14:15], v[16:17] op_sel:[0,0,0] op_sel_hi:[1,0,1]
	v_pk_fma_f32 v[18:19], v[50:51], v[14:15], v[18:19] op_sel:[0,0,0] op_sel_hi:[1,0,1]
	v_pk_fma_f32 v[20:21], v[52:53], v[14:15], v[20:21] op_sel:[0,0,0] op_sel_hi:[1,0,1]
	v_pk_fma_f32 v[22:23], v[54:55], v[14:15], v[22:23] op_sel:[0,0,0] op_sel_hi:[1,0,1]
	v_pk_fma_f32 v[24:25], v[56:57], v[14:15], v[24:25] op_sel:[0,0,0] op_sel_hi:[1,0,1]
	v_pk_fma_f32 v[26:27], v[58:59], v[14:15], v[26:27] op_sel:[0,0,0] op_sel_hi:[1,0,1]
	v_pk_fma_f32 v[28:29], v[60:61], v[14:15], v[28:29] op_sel:[0,0,0] op_sel_hi:[1,0,1]
	v_pk_fma_f32 v[30:31], v[62:63], v[14:15], v[30:31] op_sel:[0,0,0] op_sel_hi:[1,0,1]
	v_pk_fma_f32 v[32:33], v[64:65], v[14:15], v[32:33] op_sel:[0,0,0] op_sel_hi:[1,0,1]
	v_pk_fma_f32 v[34:35], v[66:67], v[14:15], v[34:35] op_sel:[0,0,0] op_sel_hi:[1,0,1]
	v_pk_fma_f32 v[36:37], v[68:69], v[14:15], v[36:37] op_sel:[0,0,0] op_sel_hi:[1,0,1]
	v_pk_fma_f32 v[38:39], v[70:71], v[14:15], v[38:39] op_sel:[0,0,0] op_sel_hi:[1,0,1]
	v_pk_fma_f32 v[40:41], v[72:73], v[14:15], v[40:41] op_sel:[0,0,0] op_sel_hi:[1,0,1]
	ds_read_b128 v[46:49], v1 offset:44912
	ds_read_b128 v[50:53], v1 offset:44928
	ds_read_b128 v[54:57], v1 offset:44944
	ds_read_b128 v[58:61], v1 offset:44960
	ds_read_b128 v[62:65], v1 offset:44976
	ds_read_b128 v[66:69], v1 offset:44992
	ds_read_b128 v[70:73], v1 offset:45008
	s_waitcnt lgkmcnt(7)
	v_pk_fma_f32 v[16:17], v[80:81], v[14:15], v[16:17] op_sel:[0,1,0] op_sel_hi:[1,1,1]
	v_pk_fma_f32 v[18:19], v[82:83], v[14:15], v[18:19] op_sel:[0,1,0] op_sel_hi:[1,1,1]
	v_pk_fma_f32 v[20:21], v[84:85], v[14:15], v[20:21] op_sel:[0,1,0] op_sel_hi:[1,1,1]
	v_pk_fma_f32 v[22:23], v[86:87], v[14:15], v[22:23] op_sel:[0,1,0] op_sel_hi:[1,1,1]
	v_pk_fma_f32 v[24:25], v[88:89], v[14:15], v[24:25] op_sel:[0,1,0] op_sel_hi:[1,1,1]
	v_pk_fma_f32 v[26:27], v[226:227], v[14:15], v[26:27] op_sel:[0,1,0] op_sel_hi:[1,1,1]
	v_pk_fma_f32 v[28:29], v[228:229], v[14:15], v[28:29] op_sel:[0,1,0] op_sel_hi:[1,1,1]
	v_pk_fma_f32 v[30:31], v[230:231], v[14:15], v[30:31] op_sel:[0,1,0] op_sel_hi:[1,1,1]
	v_pk_fma_f32 v[32:33], v[232:233], v[14:15], v[32:33] op_sel:[0,1,0] op_sel_hi:[1,1,1]
	v_pk_fma_f32 v[34:35], v[234:235], v[14:15], v[34:35] op_sel:[0,1,0] op_sel_hi:[1,1,1]
	v_pk_fma_f32 v[36:37], v[236:237], v[14:15], v[36:37] op_sel:[0,1,0] op_sel_hi:[1,1,1]
	v_pk_fma_f32 v[38:39], v[238:239], v[14:15], v[38:39] op_sel:[0,1,0] op_sel_hi:[1,1,1]
	v_pk_fma_f32 v[40:41], v[240:241], v[14:15], v[40:41] op_sel:[0,1,0] op_sel_hi:[1,1,1]
	ds_read_b128 v[82:85], v1 offset:45072
	ds_read_b128 v[86:89], v1 offset:45088
	ds_read_b128 v[226:229], v1 offset:45104
	ds_read_b128 v[230:233], v1 offset:45120
	ds_read_b128 v[234:237], v1 offset:45136
	ds_read_b128 v[238:241], v1 offset:45152
	s_waitcnt lgkmcnt(6)
	v_fmac_f32_e32 v17, v49, v16
	v_pk_fma_f32 v[18:19], v[50:51], v[16:17], v[18:19] op_sel:[0,0,0] op_sel_hi:[1,0,1]
	v_pk_fma_f32 v[20:21], v[52:53], v[16:17], v[20:21] op_sel:[0,0,0] op_sel_hi:[1,0,1]
	v_pk_fma_f32 v[22:23], v[54:55], v[16:17], v[22:23] op_sel:[0,0,0] op_sel_hi:[1,0,1]
	v_pk_fma_f32 v[24:25], v[56:57], v[16:17], v[24:25] op_sel:[0,0,0] op_sel_hi:[1,0,1]
	v_pk_fma_f32 v[26:27], v[58:59], v[16:17], v[26:27] op_sel:[0,0,0] op_sel_hi:[1,0,1]
	v_pk_fma_f32 v[28:29], v[60:61], v[16:17], v[28:29] op_sel:[0,0,0] op_sel_hi:[1,0,1]
	v_pk_fma_f32 v[30:31], v[62:63], v[16:17], v[30:31] op_sel:[0,0,0] op_sel_hi:[1,0,1]
	v_pk_fma_f32 v[32:33], v[64:65], v[16:17], v[32:33] op_sel:[0,0,0] op_sel_hi:[1,0,1]
	v_pk_fma_f32 v[34:35], v[66:67], v[16:17], v[34:35] op_sel:[0,0,0] op_sel_hi:[1,0,1]
	v_pk_fma_f32 v[36:37], v[68:69], v[16:17], v[36:37] op_sel:[0,0,0] op_sel_hi:[1,0,1]
	v_pk_fma_f32 v[38:39], v[70:71], v[16:17], v[38:39] op_sel:[0,0,0] op_sel_hi:[1,0,1]
	v_pk_fma_f32 v[40:41], v[72:73], v[16:17], v[40:41] op_sel:[0,0,0] op_sel_hi:[1,0,1]
	ds_read_b128 v[50:53], v1 offset:45216
	ds_read_b128 v[54:57], v1 offset:45232
	ds_read_b128 v[58:61], v1 offset:45248
	ds_read_b128 v[62:65], v1 offset:45264
	ds_read_b128 v[66:69], v1 offset:45280
	ds_read_b128 v[70:73], v1 offset:45296
	s_waitcnt lgkmcnt(6)
	v_pk_fma_f32 v[18:19], v[82:83], v[16:17], v[18:19] op_sel:[0,1,0] op_sel_hi:[1,1,1]
	v_pk_fma_f32 v[20:21], v[84:85], v[16:17], v[20:21] op_sel:[0,1,0] op_sel_hi:[1,1,1]
	v_pk_fma_f32 v[22:23], v[86:87], v[16:17], v[22:23] op_sel:[0,1,0] op_sel_hi:[1,1,1]
	v_pk_fma_f32 v[24:25], v[88:89], v[16:17], v[24:25] op_sel:[0,1,0] op_sel_hi:[1,1,1]
	v_pk_fma_f32 v[26:27], v[226:227], v[16:17], v[26:27] op_sel:[0,1,0] op_sel_hi:[1,1,1]
	v_pk_fma_f32 v[28:29], v[228:229], v[16:17], v[28:29] op_sel:[0,1,0] op_sel_hi:[1,1,1]
	v_pk_fma_f32 v[30:31], v[230:231], v[16:17], v[30:31] op_sel:[0,1,0] op_sel_hi:[1,1,1]
	v_pk_fma_f32 v[32:33], v[232:233], v[16:17], v[32:33] op_sel:[0,1,0] op_sel_hi:[1,1,1]
	v_pk_fma_f32 v[34:35], v[234:235], v[16:17], v[34:35] op_sel:[0,1,0] op_sel_hi:[1,1,1]
	v_pk_fma_f32 v[36:37], v[236:237], v[16:17], v[36:37] op_sel:[0,1,0] op_sel_hi:[1,1,1]
	v_pk_fma_f32 v[38:39], v[238:239], v[16:17], v[38:39] op_sel:[0,1,0] op_sel_hi:[1,1,1]
	v_pk_fma_f32 v[40:41], v[240:241], v[16:17], v[40:41] op_sel:[0,1,0] op_sel_hi:[1,1,1]
	ds_read_b128 v[82:85], v1 offset:45360
	ds_read_b128 v[86:89], v1 offset:45376
	ds_read_b128 v[226:229], v1 offset:45392
	ds_read_b128 v[230:233], v1 offset:45408
	ds_read_b128 v[234:237], v1 offset:45424
	ds_read_b128 v[238:241], v1 offset:45440
	s_waitcnt lgkmcnt(6)
	v_fmac_f32_e32 v19, v51, v18
	v_pk_fma_f32 v[20:21], v[52:53], v[18:19], v[20:21] op_sel:[0,0,0] op_sel_hi:[1,0,1]
	v_pk_fma_f32 v[22:23], v[54:55], v[18:19], v[22:23] op_sel:[0,0,0] op_sel_hi:[1,0,1]
	v_pk_fma_f32 v[24:25], v[56:57], v[18:19], v[24:25] op_sel:[0,0,0] op_sel_hi:[1,0,1]
	v_pk_fma_f32 v[26:27], v[58:59], v[18:19], v[26:27] op_sel:[0,0,0] op_sel_hi:[1,0,1]
	v_pk_fma_f32 v[28:29], v[60:61], v[18:19], v[28:29] op_sel:[0,0,0] op_sel_hi:[1,0,1]
	v_pk_fma_f32 v[30:31], v[62:63], v[18:19], v[30:31] op_sel:[0,0,0] op_sel_hi:[1,0,1]
	v_pk_fma_f32 v[32:33], v[64:65], v[18:19], v[32:33] op_sel:[0,0,0] op_sel_hi:[1,0,1]
	v_pk_fma_f32 v[34:35], v[66:67], v[18:19], v[34:35] op_sel:[0,0,0] op_sel_hi:[1,0,1]
	v_pk_fma_f32 v[36:37], v[68:69], v[18:19], v[36:37] op_sel:[0,0,0] op_sel_hi:[1,0,1]
	v_pk_fma_f32 v[38:39], v[70:71], v[18:19], v[38:39] op_sel:[0,0,0] op_sel_hi:[1,0,1]
	v_pk_fma_f32 v[40:41], v[72:73], v[18:19], v[40:41] op_sel:[0,0,0] op_sel_hi:[1,0,1]
	ds_read_b128 v[50:53], v1 offset:45504
	ds_read_b128 v[54:57], v1 offset:45520
	ds_read_b128 v[58:61], v1 offset:45536
	ds_read_b128 v[62:65], v1 offset:45552
	ds_read_b128 v[66:69], v1 offset:45568
	ds_read_b128 v[70:73], v1 offset:45584
	s_waitcnt lgkmcnt(6)
	v_pk_fma_f32 v[20:21], v[84:85], v[18:19], v[20:21] op_sel:[0,1,0] op_sel_hi:[1,1,1]
	v_pk_fma_f32 v[22:23], v[86:87], v[18:19], v[22:23] op_sel:[0,1,0] op_sel_hi:[1,1,1]
	v_pk_fma_f32 v[24:25], v[88:89], v[18:19], v[24:25] op_sel:[0,1,0] op_sel_hi:[1,1,1]
	v_pk_fma_f32 v[26:27], v[226:227], v[18:19], v[26:27] op_sel:[0,1,0] op_sel_hi:[1,1,1]
	v_pk_fma_f32 v[28:29], v[228:229], v[18:19], v[28:29] op_sel:[0,1,0] op_sel_hi:[1,1,1]
	v_pk_fma_f32 v[30:31], v[230:231], v[18:19], v[30:31] op_sel:[0,1,0] op_sel_hi:[1,1,1]
	v_pk_fma_f32 v[32:33], v[232:233], v[18:19], v[32:33] op_sel:[0,1,0] op_sel_hi:[1,1,1]
	v_pk_fma_f32 v[34:35], v[234:235], v[18:19], v[34:35] op_sel:[0,1,0] op_sel_hi:[1,1,1]
	v_pk_fma_f32 v[36:37], v[236:237], v[18:19], v[36:37] op_sel:[0,1,0] op_sel_hi:[1,1,1]
	v_pk_fma_f32 v[38:39], v[238:239], v[18:19], v[38:39] op_sel:[0,1,0] op_sel_hi:[1,1,1]
	v_pk_fma_f32 v[40:41], v[240:241], v[18:19], v[40:41] op_sel:[0,1,0] op_sel_hi:[1,1,1]
	ds_read_b128 v[86:89], v1 offset:45664
	ds_read_b128 v[226:229], v1 offset:45680
	ds_read_b128 v[230:233], v1 offset:45696
	ds_read_b128 v[234:237], v1 offset:45712
	ds_read_b128 v[238:241], v1 offset:45728
	s_waitcnt lgkmcnt(5)
	v_fmac_f32_e32 v21, v53, v20
	v_pk_fma_f32 v[22:23], v[54:55], v[20:21], v[22:23] op_sel:[0,0,0] op_sel_hi:[1,0,1]
	v_pk_fma_f32 v[24:25], v[56:57], v[20:21], v[24:25] op_sel:[0,0,0] op_sel_hi:[1,0,1]
	v_pk_fma_f32 v[26:27], v[58:59], v[20:21], v[26:27] op_sel:[0,0,0] op_sel_hi:[1,0,1]
	v_pk_fma_f32 v[28:29], v[60:61], v[20:21], v[28:29] op_sel:[0,0,0] op_sel_hi:[1,0,1]
	v_pk_fma_f32 v[30:31], v[62:63], v[20:21], v[30:31] op_sel:[0,0,0] op_sel_hi:[1,0,1]
	v_pk_fma_f32 v[32:33], v[64:65], v[20:21], v[32:33] op_sel:[0,0,0] op_sel_hi:[1,0,1]
	v_pk_fma_f32 v[34:35], v[66:67], v[20:21], v[34:35] op_sel:[0,0,0] op_sel_hi:[1,0,1]
	v_pk_fma_f32 v[36:37], v[68:69], v[20:21], v[36:37] op_sel:[0,0,0] op_sel_hi:[1,0,1]
	v_pk_fma_f32 v[38:39], v[70:71], v[20:21], v[38:39] op_sel:[0,0,0] op_sel_hi:[1,0,1]
	v_pk_fma_f32 v[40:41], v[72:73], v[20:21], v[40:41] op_sel:[0,0,0] op_sel_hi:[1,0,1]
	ds_read_b128 v[54:57], v1 offset:45808
	ds_read_b128 v[58:61], v1 offset:45824
	ds_read_b128 v[62:65], v1 offset:45840
	ds_read_b128 v[66:69], v1 offset:45856
	ds_read_b128 v[70:73], v1 offset:45872
	s_waitcnt lgkmcnt(5)
	v_pk_fma_f32 v[22:23], v[86:87], v[20:21], v[22:23] op_sel:[0,1,0] op_sel_hi:[1,1,1]
	v_pk_fma_f32 v[24:25], v[88:89], v[20:21], v[24:25] op_sel:[0,1,0] op_sel_hi:[1,1,1]
	v_pk_fma_f32 v[26:27], v[226:227], v[20:21], v[26:27] op_sel:[0,1,0] op_sel_hi:[1,1,1]
	v_pk_fma_f32 v[28:29], v[228:229], v[20:21], v[28:29] op_sel:[0,1,0] op_sel_hi:[1,1,1]
	v_pk_fma_f32 v[30:31], v[230:231], v[20:21], v[30:31] op_sel:[0,1,0] op_sel_hi:[1,1,1]
	v_pk_fma_f32 v[32:33], v[232:233], v[20:21], v[32:33] op_sel:[0,1,0] op_sel_hi:[1,1,1]
	v_pk_fma_f32 v[34:35], v[234:235], v[20:21], v[34:35] op_sel:[0,1,0] op_sel_hi:[1,1,1]
	v_pk_fma_f32 v[36:37], v[236:237], v[20:21], v[36:37] op_sel:[0,1,0] op_sel_hi:[1,1,1]
	v_pk_fma_f32 v[38:39], v[238:239], v[20:21], v[38:39] op_sel:[0,1,0] op_sel_hi:[1,1,1]
	v_pk_fma_f32 v[40:41], v[240:241], v[20:21], v[40:41] op_sel:[0,1,0] op_sel_hi:[1,1,1]
	ds_read_b128 v[86:89], v1 offset:45952
	ds_read_b128 v[226:229], v1 offset:45968
	ds_read_b128 v[230:233], v1 offset:45984
	ds_read_b128 v[234:237], v1 offset:46000
	ds_read_b128 v[238:241], v1 offset:46016
	s_waitcnt lgkmcnt(5)
	v_fmac_f32_e32 v23, v55, v22
	v_pk_fma_f32 v[24:25], v[56:57], v[22:23], v[24:25] op_sel:[0,0,0] op_sel_hi:[1,0,1]
	v_pk_fma_f32 v[26:27], v[58:59], v[22:23], v[26:27] op_sel:[0,0,0] op_sel_hi:[1,0,1]
	v_pk_fma_f32 v[28:29], v[60:61], v[22:23], v[28:29] op_sel:[0,0,0] op_sel_hi:[1,0,1]
	v_pk_fma_f32 v[30:31], v[62:63], v[22:23], v[30:31] op_sel:[0,0,0] op_sel_hi:[1,0,1]
	v_pk_fma_f32 v[32:33], v[64:65], v[22:23], v[32:33] op_sel:[0,0,0] op_sel_hi:[1,0,1]
	v_pk_fma_f32 v[34:35], v[66:67], v[22:23], v[34:35] op_sel:[0,0,0] op_sel_hi:[1,0,1]
	v_pk_fma_f32 v[36:37], v[68:69], v[22:23], v[36:37] op_sel:[0,0,0] op_sel_hi:[1,0,1]
	v_pk_fma_f32 v[38:39], v[70:71], v[22:23], v[38:39] op_sel:[0,0,0] op_sel_hi:[1,0,1]
	v_pk_fma_f32 v[40:41], v[72:73], v[22:23], v[40:41] op_sel:[0,0,0] op_sel_hi:[1,0,1]
	ds_read_b128 v[54:57], v1 offset:46096
	ds_read_b128 v[58:61], v1 offset:46112
	ds_read_b128 v[62:65], v1 offset:46128
	ds_read_b128 v[66:69], v1 offset:46144
	ds_read_b128 v[70:73], v1 offset:46160
	s_waitcnt lgkmcnt(5)
	v_pk_fma_f32 v[24:25], v[88:89], v[22:23], v[24:25] op_sel:[0,1,0] op_sel_hi:[1,1,1]
	v_pk_fma_f32 v[26:27], v[226:227], v[22:23], v[26:27] op_sel:[0,1,0] op_sel_hi:[1,1,1]
	v_pk_fma_f32 v[28:29], v[228:229], v[22:23], v[28:29] op_sel:[0,1,0] op_sel_hi:[1,1,1]
	v_pk_fma_f32 v[30:31], v[230:231], v[22:23], v[30:31] op_sel:[0,1,0] op_sel_hi:[1,1,1]
	v_pk_fma_f32 v[32:33], v[232:233], v[22:23], v[32:33] op_sel:[0,1,0] op_sel_hi:[1,1,1]
	v_pk_fma_f32 v[34:35], v[234:235], v[22:23], v[34:35] op_sel:[0,1,0] op_sel_hi:[1,1,1]
	v_pk_fma_f32 v[36:37], v[236:237], v[22:23], v[36:37] op_sel:[0,1,0] op_sel_hi:[1,1,1]
	v_pk_fma_f32 v[38:39], v[238:239], v[22:23], v[38:39] op_sel:[0,1,0] op_sel_hi:[1,1,1]
	v_pk_fma_f32 v[40:41], v[240:241], v[22:23], v[40:41] op_sel:[0,1,0] op_sel_hi:[1,1,1]
	ds_read_b128 v[226:229], v1 offset:46256
	ds_read_b128 v[230:233], v1 offset:46272
	ds_read_b128 v[234:237], v1 offset:46288
	ds_read_b128 v[238:241], v1 offset:46304
	s_waitcnt lgkmcnt(4)
	v_fmac_f32_e32 v25, v57, v24
	v_pk_fma_f32 v[26:27], v[58:59], v[24:25], v[26:27] op_sel:[0,0,0] op_sel_hi:[1,0,1]
	v_pk_fma_f32 v[28:29], v[60:61], v[24:25], v[28:29] op_sel:[0,0,0] op_sel_hi:[1,0,1]
	v_pk_fma_f32 v[30:31], v[62:63], v[24:25], v[30:31] op_sel:[0,0,0] op_sel_hi:[1,0,1]
	v_pk_fma_f32 v[32:33], v[64:65], v[24:25], v[32:33] op_sel:[0,0,0] op_sel_hi:[1,0,1]
	v_pk_fma_f32 v[34:35], v[66:67], v[24:25], v[34:35] op_sel:[0,0,0] op_sel_hi:[1,0,1]
	v_pk_fma_f32 v[36:37], v[68:69], v[24:25], v[36:37] op_sel:[0,0,0] op_sel_hi:[1,0,1]
	v_pk_fma_f32 v[38:39], v[70:71], v[24:25], v[38:39] op_sel:[0,0,0] op_sel_hi:[1,0,1]
	v_pk_fma_f32 v[40:41], v[72:73], v[24:25], v[40:41] op_sel:[0,0,0] op_sel_hi:[1,0,1]
	ds_read_b128 v[58:61], v1 offset:46400
	ds_read_b128 v[62:65], v1 offset:46416
	ds_read_b128 v[66:69], v1 offset:46432
	ds_read_b128 v[70:73], v1 offset:46448
	s_waitcnt lgkmcnt(4)
	v_pk_fma_f32 v[26:27], v[226:227], v[24:25], v[26:27] op_sel:[0,1,0] op_sel_hi:[1,1,1]
	v_pk_fma_f32 v[28:29], v[228:229], v[24:25], v[28:29] op_sel:[0,1,0] op_sel_hi:[1,1,1]
	v_pk_fma_f32 v[30:31], v[230:231], v[24:25], v[30:31] op_sel:[0,1,0] op_sel_hi:[1,1,1]
	v_pk_fma_f32 v[32:33], v[232:233], v[24:25], v[32:33] op_sel:[0,1,0] op_sel_hi:[1,1,1]
	v_pk_fma_f32 v[34:35], v[234:235], v[24:25], v[34:35] op_sel:[0,1,0] op_sel_hi:[1,1,1]
	v_pk_fma_f32 v[36:37], v[236:237], v[24:25], v[36:37] op_sel:[0,1,0] op_sel_hi:[1,1,1]
	v_pk_fma_f32 v[38:39], v[238:239], v[24:25], v[38:39] op_sel:[0,1,0] op_sel_hi:[1,1,1]
	v_pk_fma_f32 v[40:41], v[240:241], v[24:25], v[40:41] op_sel:[0,1,0] op_sel_hi:[1,1,1]
	ds_read_b128 v[226:229], v1 offset:46544
	ds_read_b128 v[230:233], v1 offset:46560
	ds_read_b128 v[234:237], v1 offset:46576
	ds_read_b128 v[238:241], v1 offset:46592
	s_waitcnt lgkmcnt(4)
	v_fmac_f32_e32 v27, v59, v26
	v_pk_fma_f32 v[28:29], v[60:61], v[26:27], v[28:29] op_sel:[0,0,0] op_sel_hi:[1,0,1]
	v_pk_fma_f32 v[30:31], v[62:63], v[26:27], v[30:31] op_sel:[0,0,0] op_sel_hi:[1,0,1]
	v_pk_fma_f32 v[32:33], v[64:65], v[26:27], v[32:33] op_sel:[0,0,0] op_sel_hi:[1,0,1]
	v_pk_fma_f32 v[34:35], v[66:67], v[26:27], v[34:35] op_sel:[0,0,0] op_sel_hi:[1,0,1]
	v_pk_fma_f32 v[36:37], v[68:69], v[26:27], v[36:37] op_sel:[0,0,0] op_sel_hi:[1,0,1]
	v_pk_fma_f32 v[38:39], v[70:71], v[26:27], v[38:39] op_sel:[0,0,0] op_sel_hi:[1,0,1]
	v_pk_fma_f32 v[40:41], v[72:73], v[26:27], v[40:41] op_sel:[0,0,0] op_sel_hi:[1,0,1]
	ds_read_b128 v[58:61], v1 offset:46688
	ds_read_b128 v[62:65], v1 offset:46704
	ds_read_b128 v[66:69], v1 offset:46720
	ds_read_b128 v[70:73], v1 offset:46736
	s_waitcnt lgkmcnt(4)
	v_pk_fma_f32 v[28:29], v[228:229], v[26:27], v[28:29] op_sel:[0,1,0] op_sel_hi:[1,1,1]
	v_pk_fma_f32 v[30:31], v[230:231], v[26:27], v[30:31] op_sel:[0,1,0] op_sel_hi:[1,1,1]
	v_pk_fma_f32 v[32:33], v[232:233], v[26:27], v[32:33] op_sel:[0,1,0] op_sel_hi:[1,1,1]
	v_pk_fma_f32 v[34:35], v[234:235], v[26:27], v[34:35] op_sel:[0,1,0] op_sel_hi:[1,1,1]
	v_pk_fma_f32 v[36:37], v[236:237], v[26:27], v[36:37] op_sel:[0,1,0] op_sel_hi:[1,1,1]
	v_pk_fma_f32 v[38:39], v[238:239], v[26:27], v[38:39] op_sel:[0,1,0] op_sel_hi:[1,1,1]
	v_pk_fma_f32 v[40:41], v[240:241], v[26:27], v[40:41] op_sel:[0,1,0] op_sel_hi:[1,1,1]
	ds_read_b128 v[230:233], v1 offset:46848
	ds_read_b128 v[234:237], v1 offset:46864
	ds_read_b128 v[238:241], v1 offset:46880
	s_waitcnt lgkmcnt(3)
	v_fmac_f32_e32 v29, v61, v28
	v_pk_fma_f32 v[30:31], v[62:63], v[28:29], v[30:31] op_sel:[0,0,0] op_sel_hi:[1,0,1]
	v_pk_fma_f32 v[32:33], v[64:65], v[28:29], v[32:33] op_sel:[0,0,0] op_sel_hi:[1,0,1]
	v_pk_fma_f32 v[34:35], v[66:67], v[28:29], v[34:35] op_sel:[0,0,0] op_sel_hi:[1,0,1]
	v_pk_fma_f32 v[36:37], v[68:69], v[28:29], v[36:37] op_sel:[0,0,0] op_sel_hi:[1,0,1]
	v_pk_fma_f32 v[38:39], v[70:71], v[28:29], v[38:39] op_sel:[0,0,0] op_sel_hi:[1,0,1]
	v_pk_fma_f32 v[40:41], v[72:73], v[28:29], v[40:41] op_sel:[0,0,0] op_sel_hi:[1,0,1]
	ds_read_b128 v[62:65], v1 offset:46992
	ds_read_b128 v[66:69], v1 offset:47008
	ds_read_b128 v[70:73], v1 offset:47024
	s_waitcnt lgkmcnt(3)
	v_pk_fma_f32 v[30:31], v[230:231], v[28:29], v[30:31] op_sel:[0,1,0] op_sel_hi:[1,1,1]
	v_pk_fma_f32 v[32:33], v[232:233], v[28:29], v[32:33] op_sel:[0,1,0] op_sel_hi:[1,1,1]
	v_pk_fma_f32 v[34:35], v[234:235], v[28:29], v[34:35] op_sel:[0,1,0] op_sel_hi:[1,1,1]
	v_pk_fma_f32 v[36:37], v[236:237], v[28:29], v[36:37] op_sel:[0,1,0] op_sel_hi:[1,1,1]
	v_pk_fma_f32 v[38:39], v[238:239], v[28:29], v[38:39] op_sel:[0,1,0] op_sel_hi:[1,1,1]
	v_pk_fma_f32 v[40:41], v[240:241], v[28:29], v[40:41] op_sel:[0,1,0] op_sel_hi:[1,1,1]
	ds_read_b128 v[230:233], v1 offset:47136
	ds_read_b128 v[234:237], v1 offset:47152
	ds_read_b128 v[238:241], v1 offset:47168
	s_waitcnt lgkmcnt(3)
	v_fmac_f32_e32 v31, v63, v30
	v_pk_fma_f32 v[32:33], v[64:65], v[30:31], v[32:33] op_sel:[0,0,0] op_sel_hi:[1,0,1]
	v_pk_fma_f32 v[34:35], v[66:67], v[30:31], v[34:35] op_sel:[0,0,0] op_sel_hi:[1,0,1]
	v_pk_fma_f32 v[36:37], v[68:69], v[30:31], v[36:37] op_sel:[0,0,0] op_sel_hi:[1,0,1]
	v_pk_fma_f32 v[38:39], v[70:71], v[30:31], v[38:39] op_sel:[0,0,0] op_sel_hi:[1,0,1]
	v_pk_fma_f32 v[40:41], v[72:73], v[30:31], v[40:41] op_sel:[0,0,0] op_sel_hi:[1,0,1]
	ds_read_b128 v[62:65], v1 offset:47280
	ds_read_b128 v[66:69], v1 offset:47296
	ds_read_b128 v[70:73], v1 offset:47312
	s_waitcnt lgkmcnt(3)
	v_pk_fma_f32 v[32:33], v[232:233], v[30:31], v[32:33] op_sel:[0,1,0] op_sel_hi:[1,1,1]
	v_pk_fma_f32 v[34:35], v[234:235], v[30:31], v[34:35] op_sel:[0,1,0] op_sel_hi:[1,1,1]
	v_pk_fma_f32 v[36:37], v[236:237], v[30:31], v[36:37] op_sel:[0,1,0] op_sel_hi:[1,1,1]
	v_pk_fma_f32 v[38:39], v[238:239], v[30:31], v[38:39] op_sel:[0,1,0] op_sel_hi:[1,1,1]
	v_pk_fma_f32 v[40:41], v[240:241], v[30:31], v[40:41] op_sel:[0,1,0] op_sel_hi:[1,1,1]
	ds_read_b128 v[234:237], v1 offset:47440
	ds_read_b128 v[238:241], v1 offset:47456
	s_waitcnt lgkmcnt(2)
	v_fmac_f32_e32 v33, v65, v32
	v_pk_fma_f32 v[34:35], v[66:67], v[32:33], v[34:35] op_sel:[0,0,0] op_sel_hi:[1,0,1]
	v_pk_fma_f32 v[36:37], v[68:69], v[32:33], v[36:37] op_sel:[0,0,0] op_sel_hi:[1,0,1]
	v_pk_fma_f32 v[38:39], v[70:71], v[32:33], v[38:39] op_sel:[0,0,0] op_sel_hi:[1,0,1]
	v_pk_fma_f32 v[40:41], v[72:73], v[32:33], v[40:41] op_sel:[0,0,0] op_sel_hi:[1,0,1]
	ds_read_b128 v[66:69], v1 offset:47584
	ds_read_b128 v[70:73], v1 offset:47600
	s_waitcnt lgkmcnt(2)
	v_pk_fma_f32 v[34:35], v[234:235], v[32:33], v[34:35] op_sel:[0,1,0] op_sel_hi:[1,1,1]
	v_pk_fma_f32 v[36:37], v[236:237], v[32:33], v[36:37] op_sel:[0,1,0] op_sel_hi:[1,1,1]
	v_pk_fma_f32 v[38:39], v[238:239], v[32:33], v[38:39] op_sel:[0,1,0] op_sel_hi:[1,1,1]
	v_pk_fma_f32 v[40:41], v[240:241], v[32:33], v[40:41] op_sel:[0,1,0] op_sel_hi:[1,1,1]
	ds_read_b128 v[234:237], v1 offset:47728
	ds_read_b128 v[238:241], v1 offset:47744
	s_waitcnt lgkmcnt(2)
	v_fmac_f32_e32 v35, v67, v34
	v_pk_fma_f32 v[36:37], v[68:69], v[34:35], v[36:37] op_sel:[0,0,0] op_sel_hi:[1,0,1]
	v_pk_fma_f32 v[38:39], v[70:71], v[34:35], v[38:39] op_sel:[0,0,0] op_sel_hi:[1,0,1]
	v_pk_fma_f32 v[40:41], v[72:73], v[34:35], v[40:41] op_sel:[0,0,0] op_sel_hi:[1,0,1]
	ds_read_b128 v[66:69], v1 offset:47872
	ds_read_b128 v[70:73], v1 offset:47888
	s_waitcnt lgkmcnt(2)
	v_pk_fma_f32 v[36:37], v[236:237], v[34:35], v[36:37] op_sel:[0,1,0] op_sel_hi:[1,1,1]
	v_pk_fma_f32 v[38:39], v[238:239], v[34:35], v[38:39] op_sel:[0,1,0] op_sel_hi:[1,1,1]
	v_pk_fma_f32 v[40:41], v[240:241], v[34:35], v[40:41] op_sel:[0,1,0] op_sel_hi:[1,1,1]
	ds_read_b128 v[238:241], v1 offset:48032
	s_waitcnt lgkmcnt(1)
	v_fmac_f32_e32 v37, v69, v36
	v_pk_fma_f32 v[38:39], v[70:71], v[36:37], v[38:39] op_sel:[0,0,0] op_sel_hi:[1,0,1]
	v_pk_fma_f32 v[40:41], v[72:73], v[36:37], v[40:41] op_sel:[0,0,0] op_sel_hi:[1,0,1]
	ds_read_b128 v[70:73], v1 offset:48176
	s_waitcnt lgkmcnt(1)
	v_pk_fma_f32 v[38:39], v[238:239], v[36:37], v[38:39] op_sel:[0,1,0] op_sel_hi:[1,1,1]
	v_pk_fma_f32 v[40:41], v[240:241], v[36:37], v[40:41] op_sel:[0,1,0] op_sel_hi:[1,1,1]
	ds_read_b128 v[238:241], v1 offset:48320
	s_waitcnt lgkmcnt(1)
	v_fmac_f32_e32 v39, v71, v38
	v_pk_fma_f32 v[40:41], v[72:73], v[38:39], v[40:41] op_sel:[0,0,0] op_sel_hi:[1,0,1]
	ds_read_b128 v[70:73], v1 offset:48464
	s_waitcnt lgkmcnt(1)
	v_pk_fma_f32 v[40:41], v[240:241], v[38:39], v[40:41] op_sel:[0,1,0] op_sel_hi:[1,1,1]
	s_waitcnt lgkmcnt(0)
	v_fmac_f32_e32 v41, v73, v40
	ds_write_b32 v135, v10 offset:57856
	ds_write_b32 v135, v11 offset:58000
	ds_write_b32 v135, v12 offset:58144
	ds_write_b32 v135, v13 offset:58288
	ds_write_b32 v135, v14 offset:58432
	ds_write_b32 v135, v15 offset:58576
	ds_write_b32 v135, v16 offset:58720
	ds_write_b32 v135, v17 offset:58864
	ds_write_b32 v135, v18 offset:59008
	ds_write_b32 v135, v19 offset:59152
	ds_write_b32 v135, v20 offset:59296
	ds_write_b32 v135, v21 offset:59440
	ds_write_b32 v135, v22 offset:59584
	ds_write_b32 v135, v23 offset:59728
	ds_write_b32 v135, v24 offset:59872
	ds_write_b32 v135, v25 offset:60016
	ds_write_b32 v135, v26 offset:60160
	ds_write_b32 v135, v27 offset:60304
	ds_write_b32 v135, v28 offset:60448
	ds_write_b32 v135, v29 offset:60592
	ds_write_b32 v135, v30 offset:60736
	ds_write_b32 v135, v31 offset:60880
	ds_write_b32 v135, v32 offset:61024
	ds_write_b32 v135, v33 offset:61168
	ds_write_b32 v135, v34 offset:61312
	ds_write_b32 v135, v35 offset:61456
	ds_write_b32 v135, v36 offset:61600
	ds_write_b32 v135, v37 offset:61744
	ds_write_b32 v135, v38 offset:61888
	ds_write_b32 v135, v39 offset:62032
	ds_write_b32 v135, v40 offset:62176
	ds_write_b32 v135, v41 offset:62320
	s_branch .Ldc_b3
.Ldc_s2k:
	ds_read_b128 v[10:13], v224 offset:0
	ds_read_b128 v[14:17], v224 offset:16
	ds_read_b128 v[18:21], v224 offset:32
	ds_read_b128 v[22:25], v224 offset:48
	ds_read_b128 v[42:45], v224 offset:8704
	ds_read_b128 v[46:49], v224 offset:8720
	ds_read_b128 v[50:53], v224 offset:8736
	ds_read_b128 v[54:57], v224 offset:8752
	ds_read_b32 v82, v225 offset:53248
	ds_read_b32 v83, v225 offset:53392
	ds_read_b32 v84, v225 offset:53536
	ds_read_b32 v85, v225 offset:53680
	ds_read_b128 v[26:29], v224 offset:4352
	ds_read_b128 v[30:33], v224 offset:4368
	ds_read_b128 v[34:37], v224 offset:4384
	ds_read_b128 v[38:41], v224 offset:4400
	ds_read_b128 v[66:69], v224 offset:8704
	ds_read_b128 v[70:73], v224 offset:8720
	ds_read_b128 v[74:77], v224 offset:8736
	ds_read_b128 v[78:81], v224 offset:8752
	ds_read_b32 v86, v225 offset:55552
	ds_read_b32 v87, v225 offset:55696
	ds_read_b32 v88, v225 offset:55840
	ds_read_b32 v89, v225 offset:55984
	s_waitcnt lgkmcnt(12)
	v_mfma_f32_16x16x4_f32 v[58:61], v10, v42, 0
	v_mfma_f32_16x16x4_f32 v[58:61], v11, v43, v[58:61]
	v_mfma_f32_16x16x4_f32 v[58:61], v12, v44, v[58:61]
	v_mfma_f32_16x16x4_f32 v[58:61], v13, v45, v[58:61]
	v_mfma_f32_16x16x4_f32 v[58:61], v14, v46, v[58:61]
	v_mfma_f32_16x16x4_f32 v[58:61], v15, v47, v[58:61]
	v_mfma_f32_16x16x4_f32 v[58:61], v16, v48, v[58:61]
	v_mfma_f32_16x16x4_f32 v[58:61], v17, v49, v[58:61]
	v_mfma_f32_16x16x4_f32 v[58:61], v18, v50, v[58:61]
	v_mfma_f32_16x16x4_f32 v[58:61], v19, v51, v[58:61]
	v_mfma_f32_16x16x4_f32 v[58:61], v20, v52, v[58:61]
	v_mfma_f32_16x16x4_f32 v[58:61], v21, v53, v[58:61]
	v_mfma_f32_16x16x4_f32 v[58:61], v22, v54, v[58:61]
	v_mfma_f32_16x16x4_f32 v[58:61], v23, v55, v[58:61]
	v_mfma_f32_16x16x4_f32 v[58:61], v24, v56, v[58:61]
	v_mfma_f32_16x16x4_f32 v[58:61], v25, v57, v[58:61]
	ds_read_b128 v[10:13], v224 offset:4352
	ds_read_b128 v[14:17], v224 offset:4368
	ds_read_b128 v[18:21], v224 offset:4384
	ds_read_b128 v[22:25], v224 offset:4400
	ds_read_b128 v[42:45], v224 offset:13056
	ds_read_b128 v[46:49], v224 offset:13072
	ds_read_b128 v[50:53], v224 offset:13088
	ds_read_b128 v[54:57], v224 offset:13104
	ds_read_b32 v226, v225 offset:55616
	ds_read_b32 v227, v225 offset:55760
	ds_read_b32 v228, v225 offset:55904
	ds_read_b32 v229, v225 offset:56048
	s_waitcnt lgkmcnt(12)
	v_mfma_f32_16x16x4_f32 v[62:65], v26, v66, 0
	v_mfma_f32_16x16x4_f32 v[62:65], v27, v67, v[62:65]
	v_mfma_f32_16x16x4_f32 v[62:65], v28, v68, v[62:65]
	v_mfma_f32_16x16x4_f32 v[62:65], v29, v69, v[62:65]
	v_mfma_f32_16x16x4_f32 v[62:65], v30, v70, v[62:65]
	v_mfma_f32_16x16x4_f32 v[62:65], v31, v71, v[62:65]
	v_mfma_f32_16x16x4_f32 v[62:65], v32, v72, v[62:65]
	v_mfma_f32_16x16x4_f32 v[62:65], v33, v73, v[62:65]
	v_mfma_f32_16x16x4_f32 v[62:65], v34, v74, v[62:65]
	v_mfma_f32_16x16x4_f32 v[62:65], v35, v75, v[62:65]
	v_mfma_f32_16x16x4_f32 v[62:65], v36, v76, v[62:65]
	v_mfma_f32_16x16x4_f32 v[62:65], v37, v77, v[62:65]
	v_mfma_f32_16x16x4_f32 v[62:65], v38, v78, v[62:65]
	v_mfma_f32_16x16x4_f32 v[62:65], v39, v79, v[62:65]
	v_mfma_f32_16x16x4_f32 v[62:65], v40, v80, v[62:65]
	v_mfma_f32_16x16x4_f32 v[62:65], v41, v81, v[62:65]
	v_mul_f32_e32 v58, v58, v82
	ds_write_b32 v225, v58 offset:48640
	v_mul_f32_e32 v59, v59, v83
	ds_write_b32 v225, v59 offset:48784
	v_mul_f32_e32 v60, v60, v84
	ds_write_b32 v225, v60 offset:48928
	v_mul_f32_e32 v61, v61, v85
	ds_write_b32 v225, v61 offset:49072
	s_waitcnt lgkmcnt(0)
	v_mfma_f32_16x16x4_f32 v[58:61], v10, v42, 0
	v_mfma_f32_16x16x4_f32 v[58:61], v11, v43, v[58:61]
	v_mfma_f32_16x16x4_f32 v[58:61], v12, v44, v[58:61]
	v_mfma_f32_16x16x4_f32 v[58:61], v13, v45, v[58:61]
	v_mfma_f32_16x16x4_f32 v[58:61], v14, v46, v[58:61]
	v_mfma_f32_16x16x4_f32 v[58:61], v15, v47, v[58:61]
	v_mfma_f32_16x16x4_f32 v[58:61], v16, v48, v[58:61]
	v_mfma_f32_16x16x4_f32 v[58:61], v17, v49, v[58:61]
	v_mfma_f32_16x16x4_f32 v[58:61], v18, v50, v[58:61]
	v_mfma_f32_16x16x4_f32 v[58:61], v19, v51, v[58:61]
	v_mfma_f32_16x16x4_f32 v[58:61], v20, v52, v[58:61]
	v_mfma_f32_16x16x4_f32 v[58:61], v21, v53, v[58:61]
	v_mfma_f32_16x16x4_f32 v[58:61], v22, v54, v[58:61]
	v_mfma_f32_16x16x4_f32 v[58:61], v23, v55, v[58:61]
	v_mfma_f32_16x16x4_f32 v[58:61], v24, v56, v[58:61]
	v_mfma_f32_16x16x4_f32 v[58:61], v25, v57, v[58:61]
	v_mul_f32_e32 v62, v62, v86
	ds_write_b32 v225, v62 offset:50944
	v_mul_f32_e32 v63, v63, v87
	ds_write_b32 v225, v63 offset:51088
	v_mul_f32_e32 v64, v64, v88
	ds_write_b32 v225, v64 offset:51232
	v_mul_f32_e32 v65, v65, v89
	ds_write_b32 v225, v65 offset:51376
	s_nop 7
	s_nop 3
	v_mul_f32_e32 v58, v58, v226
	ds_write_b32 v225, v58 offset:51008
	v_mul_f32_e32 v59, v59, v227
	ds_write_b32 v225, v59 offset:51152
	v_mul_f32_e32 v60, v60, v228
	ds_write_b32 v225, v60 offset:51296
	v_mul_f32_e32 v61, v61, v229
	ds_write_b32 v225, v61 offset:51440
	s_branch .Ldc_b3
.Ldc_s2q:
	s_and_b32 s61, s60, 1
	s_lshl_b32 s61, s61, 6
	v_mul_u32_u24_e32 v244, 0x840, v223
	v_lshl_add_u32 v244, v222, 2, v244
	s_add_i32 s61, s61, 0x11600
	v_add_u32_e32 v244, s61, v244
	ds_read_b32 v10, v244 offset:0
	ds_read_b32 v11, v244 offset:132
	ds_read_b32 v12, v244 offset:264
	ds_read_b32 v13, v244 offset:396
	ds_read_b32 v14, v244 offset:528
	ds_read_b32 v15, v244 offset:660
	ds_read_b32 v16, v244 offset:792
	ds_read_b32 v17, v244 offset:924
	ds_read_b32 v18, v244 offset:1056
	ds_read_b32 v19, v244 offset:1188
	ds_read_b32 v20, v244 offset:1320
	ds_read_b32 v21, v244 offset:1452
	ds_read_b32 v22, v244 offset:1584
	ds_read_b32 v23, v244 offset:1716
	ds_read_b32 v24, v244 offset:1848
	ds_read_b32 v25, v244 offset:1980
	ds_read_b128 v[26:29], v224 offset:0
	ds_read_b128 v[30:33], v224 offset:16
	ds_read_b128 v[34:37], v224 offset:32
	ds_read_b128 v[38:41], v224 offset:48
	v_lshlrev_b32_e32 v245, 2, v222
	v_add_u32_e32 v245, 0x13700, v245
	ds_read_b32 v42, v245 offset:0
	s_waitcnt lgkmcnt(0)
	v_mul_f32_e32 v26, v42, v26
	v_mul_f32_e32 v27, v42, v27
	v_mul_f32_e32 v28, v42, v28
	v_mul_f32_e32 v29, v42, v29
	v_mul_f32_e32 v30, v42, v30
	v_mul_f32_e32 v31, v42, v31
	v_mul_f32_e32 v32, v42, v32
	v_mul_f32_e32 v33, v42, v33
	v_mul_f32_e32 v34, v42, v34
	v_mul_f32_e32 v35, v42, v35
	v_mul_f32_e32 v36, v42, v36
	v_mul_f32_e32 v37, v42, v37
	v_mul_f32_e32 v38, v42, v38
	v_mul_f32_e32 v39, v42, v39
	v_mul_f32_e32 v40, v42, v40
	v_mul_f32_e32 v41, v42, v41
	s_nop 1
	v_mfma_f32_16x16x4_f32 v[58:61], v26, v10, 0
	v_mfma_f32_16x16x4_f32 v[58:61], v27, v11, v[58:61]
	v_mfma_f32_16x16x4_f32 v[58:61], v28, v12, v[58:61]
	v_mfma_f32_16x16x4_f32 v[58:61], v29, v13, v[58:61]
	v_mfma_f32_16x16x4_f32 v[58:61], v30, v14, v[58:61]
	v_mfma_f32_16x16x4_f32 v[58:61], v31, v15, v[58:61]
	v_mfma_f32_16x16x4_f32 v[58:61], v32, v16, v[58:61]
	v_mfma_f32_16x16x4_f32 v[58:61], v33, v17, v[58:61]
	v_mfma_f32_16x16x4_f32 v[58:61], v34, v18, v[58:61]
	v_mfma_f32_16x16x4_f32 v[58:61], v35, v19, v[58:61]
	v_mfma_f32_16x16x4_f32 v[58:61], v36, v20, v[58:61]
	v_mfma_f32_16x16x4_f32 v[58:61], v37, v21, v[58:61]
	v_mfma_f32_16x16x4_f32 v[58:61], v38, v22, v[58:61]
	v_mfma_f32_16x16x4_f32 v[58:61], v39, v23, v[58:61]
	v_mfma_f32_16x16x4_f32 v[58:61], v40, v24, v[58:61]
	v_mfma_f32_16x16x4_f32 v[58:61], v41, v25, v[58:61]
	ds_read_b128 v[26:29], v224 offset:4352
	ds_read_b128 v[30:33], v224 offset:4368
	ds_read_b128 v[34:37], v224 offset:4384
	ds_read_b128 v[38:41], v224 offset:4400
	v_lshlrev_b32_e32 v245, 2, v222
	v_add_u32_e32 v245, 0x13700, v245
	ds_read_b32 v42, v245 offset:64
	s_waitcnt lgkmcnt(0)
	v_mul_f32_e32 v26, v42, v26
	v_mul_f32_e32 v27, v42, v27
	v_mul_f32_e32 v28, v42, v28
	v_mul_f32_e32 v29, v42, v29
	v_mul_f32_e32 v30, v42, v30
	v_mul_f32_e32 v31, v42, v31
	v_mul_f32_e32 v32, v42, v32
	v_mul_f32_e32 v33, v42, v33
	v_mul_f32_e32 v34, v42, v34
	v_mul_f32_e32 v35, v42, v35
	v_mul_f32_e32 v36, v42, v36
	v_mul_f32_e32 v37, v42, v37
	v_mul_f32_e32 v38, v42, v38
	v_mul_f32_e32 v39, v42, v39
	v_mul_f32_e32 v40, v42, v40
	v_mul_f32_e32 v41, v42, v41
	s_nop 1
	v_mfma_f32_16x16x4_f32 v[62:65], v26, v10, 0
	v_mfma_f32_16x16x4_f32 v[62:65], v27, v11, v[62:65]
	v_mfma_f32_16x16x4_f32 v[62:65], v28, v12, v[62:65]
	v_mfma_f32_16x16x4_f32 v[62:65], v29, v13, v[62:65]
	v_mfma_f32_16x16x4_f32 v[62:65], v30, v14, v[62:65]
	v_mfma_f32_16x16x4_f32 v[62:65], v31, v15, v[62:65]
	v_mfma_f32_16x16x4_f32 v[62:65], v32, v16, v[62:65]
	v_mfma_f32_16x16x4_f32 v[62:65], v33, v17, v[62:65]
	v_mfma_f32_16x16x4_f32 v[62:65], v34, v18, v[62:65]
	v_mfma_f32_16x16x4_f32 v[62:65], v35, v19, v[62:65]
	v_mfma_f32_16x16x4_f32 v[62:65], v36, v20, v[62:65]
	v_mfma_f32_16x16x4_f32 v[62:65], v37, v21, v[62:65]
	v_mfma_f32_16x16x4_f32 v[62:65], v38, v22, v[62:65]
	v_mfma_f32_16x16x4_f32 v[62:65], v39, v23, v[62:65]
	v_mfma_f32_16x16x4_f32 v[62:65], v40, v24, v[62:65]
	v_mfma_f32_16x16x4_f32 v[62:65], v41, v25, v[62:65]
.Ldc_b3:
	s_waitcnt lgkmcnt(0)
	s_barrier
	s_cmp_lt_u32 s60, 2
	s_cbranch_scc1 .Ldc_s4w
	s_and_b32 s61, s60, 1
	s_lshl_b32 s61, s61, 6
	v_mul_u32_u24_e32 v244, 0x480, v223
	v_lshl_add_u32 v244, v222, 2, v244
	v_add_u32_e32 v244, s61, v244
	ds_read_b32 v34, v244 offset:57856
	ds_read_b32 v35, v244 offset:58000
	ds_read_b32 v36, v244 offset:58144
	ds_read_b32 v37, v244 offset:58288
	ds_read_b32 v38, v244 offset:58432
	ds_read_b32 v39, v244 offset:58576
	ds_read_b32 v40, v244 offset:58720
	ds_read_b32 v41, v244 offset:58864
	v_mul_u32_u24_e32 v245, 0x90, v222
	v_lshl_add_u32 v245, v223, 5, v245
	ds_read_b128 v[26:29], v245 offset:48640
	ds_read_b128 v[30:33], v245 offset:48656
	s_waitcnt lgkmcnt(0)
	v_mfma_f32_16x16x4_f32 v[58:61], v26, v34, v[58:61]
	v_mfma_f32_16x16x4_f32 v[58:61], v27, v35, v[58:61]
	v_mfma_f32_16x16x4_f32 v[58:61], v28, v36, v[58:61]
	v_mfma_f32_16x16x4_f32 v[58:61], v29, v37, v[58:61]
	v_mfma_f32_16x16x4_f32 v[58:61], v30, v38, v[58:61]
	v_mfma_f32_16x16x4_f32 v[58:61], v31, v39, v[58:61]
	v_mfma_f32_16x16x4_f32 v[58:61], v32, v40, v[58:61]
	v_mfma_f32_16x16x4_f32 v[58:61], v33, v41, v[58:61]
	ds_read_b128 v[26:29], v245 offset:50944
	ds_read_b128 v[30:33], v245 offset:50960
	s_waitcnt lgkmcnt(0)
	v_mfma_f32_16x16x4_f32 v[62:65], v26, v34, v[62:65]
	v_mfma_f32_16x16x4_f32 v[62:65], v27, v35, v[62:65]
	v_mfma_f32_16x16x4_f32 v[62:65], v28, v36, v[62:65]
	v_mfma_f32_16x16x4_f32 v[62:65], v29, v37, v[62:65]
	v_mfma_f32_16x16x4_f32 v[62:65], v30, v38, v[62:65]
	v_mfma_f32_16x16x4_f32 v[62:65], v31, v39, v[62:65]
	v_mfma_f32_16x16x4_f32 v[62:65], v32, v40, v[62:65]
	v_mfma_f32_16x16x4_f32 v[62:65], v33, v41, v[62:65]
	s_nop 7
	s_nop 3
	s_and_b32 s61, s60, 1
	s_lshl_b32 s61, s61, 6
	v_lshl_add_u32 v246, v223, 10, v248
	v_lshl_add_u32 v246, v222, 2, v246
	v_add_u32_e32 v246, s61, v246
	ds_write_b32 v246, v58 offset:17408
	ds_write_b32 v246, v59 offset:17664
	ds_write_b32 v246, v60 offset:17920
	ds_write_b32 v246, v61 offset:18176
	ds_write_b32 v246, v62 offset:21504
	ds_write_b32 v246, v63 offset:21760
	ds_write_b32 v246, v64 offset:22016
	ds_write_b32 v246, v65 offset:22272
	v_lshlrev_b32_e32 v245, 5, v223
	v_add_u32_e32 v245, 0x13780, v245
	ds_read_b128 v[42:45], v245
	ds_read_b128 v[46:49], v245 offset:16
	v_mov_b32_e32 v79, 0x1377c
	ds_read_b32 v78, v79
	v_mul_u32_u24_e32 v246, 0x880, v223
	v_lshl_add_u32 v246, v222, 2, v246
	s_and_b32 s61, s60, 1
	s_lshl_b32 s61, s61, 6
	s_add_i32 s61, s61, 0x11600
	v_mul_u32_u24_e32 v244, 0x210, v223
	v_lshl_add_u32 v244, v222, 2, v244
	v_add_u32_e32 v244, s61, v244
	ds_read_b32 v50, v246 offset:8896
	ds_read_b32 v51, v246 offset:9168
	ds_read_b32 v52, v246 offset:9440
	ds_read_b32 v53, v246 offset:9712
	ds_read_b32 v54, v246 offset:9984
	ds_read_b32 v55, v246 offset:10256
	ds_read_b32 v56, v246 offset:10528
	ds_read_b32 v57, v246 offset:10800
	ds_read_b32 v66, v244 offset:6336
	ds_read_b32 v67, v244 offset:6468
	ds_read_b32 v68, v244 offset:6600
	ds_read_b32 v69, v244 offset:6732
	s_waitcnt lgkmcnt(0)
	v_mul_f32_e32 v50, v42, v50
	v_mul_f32_e32 v51, v43, v51
	v_mul_f32_e32 v52, v44, v52
	v_mul_f32_e32 v53, v45, v53
	v_mul_f32_e32 v54, v46, v54
	v_mul_f32_e32 v55, v47, v55
	v_mul_f32_e32 v56, v48, v56
	v_mul_f32_e32 v57, v49, v57
	v_mul_f32_e32 v66, v78, v66
	v_mul_f32_e32 v67, v78, v67
	v_mul_f32_e32 v68, v78, v68
	v_mul_f32_e32 v69, v78, v69
	s_nop 1
	v_mfma_f32_16x16x4_f32 v[66:69], v50, v34, v[66:69]
	v_mfma_f32_16x16x4_f32 v[66:69], v51, v35, v[66:69]
	v_mfma_f32_16x16x4_f32 v[66:69], v52, v36, v[66:69]
	v_mfma_f32_16x16x4_f32 v[66:69], v53, v37, v[66:69]
	v_mfma_f32_16x16x4_f32 v[66:69], v54, v38, v[66:69]
	v_mfma_f32_16x16x4_f32 v[66:69], v55, v39, v[66:69]
	v_mfma_f32_16x16x4_f32 v[66:69], v56, v40, v[66:69]
	v_mfma_f32_16x16x4_f32 v[66:69], v57, v41, v[66:69]
	s_nop 7
	s_nop 3
	ds_write_b32 v244, v66 offset:6336
	ds_write_b32 v244, v67 offset:6468
	ds_write_b32 v244, v68 offset:6600
	ds_write_b32 v244, v69 offset:6732
	s_branch .Ldc_done
; __device__ __forceinline__ void dn_task(const Params& p, int l, int task, char* smem) {
;     ...
;     {
;       float4 k0A[2], k1A[2], q0A[2], q1A[2], abA, dtA; float2 vvA;
;       float4 k0B[2], k1B[2], q0B[2], q1B[2], abB, dtB; float2 vvB;
;       DN_LD2(0, k0A, k1A, q0A, q1A, abA, vvA, dtA);
; #pragma unroll 1
;       for (int pp = 0; pp < 16; pp += 2) {
;         DN_LD2(pp + 1, k0B, k1B, q0B, q1B, abB, vvB, dtB);
;         DN_PAIR(pp, k0A, k1A, q0A, q1A, abA, vvA, dtA);
;         const int p2 = (pp + 2 < 16) ? pp + 2 : 15;
;         DN_LD2(p2, k0A, k1A, q0A, q1A, abA, vvA, dtA);
;         DN_PAIR(pp + 1, k0B, k1B, q0B, q1B, abB, vvB, dtB);
;       }
;     }
.Ldc_s4w:
	s_and_b32 s61, s60, 1
	s_lshl_b32 s61, s61, 6
	v_mul_u32_u24_e32 v244, 0x480, v223
	v_lshl_add_u32 v244, v222, 2, v244
	v_add_u32_e32 v244, s61, v244
	ds_read_b32 v34, v244 offset:57856
	ds_read_b32 v35, v244 offset:58000
	ds_read_b32 v36, v244 offset:58144
	ds_read_b32 v37, v244 offset:58288
	ds_read_b32 v38, v244 offset:58432
	ds_read_b32 v39, v244 offset:58576
	ds_read_b32 v40, v244 offset:58720
	ds_read_b32 v41, v244 offset:58864
	v_lshlrev_b32_e32 v245, 5, v223
	v_add_u32_e32 v245, 0x13780, v245
	ds_read_b128 v[42:45], v245
	ds_read_b128 v[46:49], v245 offset:16
	v_mov_b32_e32 v79, 0x1377c
	ds_read_b32 v78, v79
	v_mul_u32_u24_e32 v246, 0x880, v223
	v_lshl_add_u32 v246, v222, 2, v246
	s_and_b32 s61, s60, 1
	s_lshl_b32 s61, s61, 6
	s_add_i32 s61, s61, 0x11600
	v_mul_u32_u24_e32 v244, 0x210, v223
	v_lshl_add_u32 v244, v222, 2, v244
	v_add_u32_e32 v244, s61, v244
	ds_read_b32 v26, v246 offset:8704
	ds_read_b32 v27, v246 offset:8976
	ds_read_b32 v28, v246 offset:9248
	ds_read_b32 v29, v246 offset:9520
	ds_read_b32 v30, v246 offset:9792
	ds_read_b32 v31, v246 offset:10064
	ds_read_b32 v32, v246 offset:10336
	ds_read_b32 v33, v246 offset:10608
	ds_read_b32 v66, v244 offset:0
	ds_read_b32 v67, v244 offset:132
	ds_read_b32 v68, v244 offset:264
	ds_read_b32 v69, v244 offset:396
	ds_read_b32 v50, v246 offset:8768
	ds_read_b32 v51, v246 offset:9040
	ds_read_b32 v52, v246 offset:9312
	ds_read_b32 v53, v246 offset:9584
	ds_read_b32 v54, v246 offset:9856
	ds_read_b32 v55, v246 offset:10128
	ds_read_b32 v56, v246 offset:10400
	ds_read_b32 v57, v246 offset:10672
	ds_read_b32 v70, v244 offset:2112
	ds_read_b32 v71, v244 offset:2244
	ds_read_b32 v72, v244 offset:2376
	ds_read_b32 v73, v244 offset:2508
	ds_read_b32 v58, v246 offset:8832
	ds_read_b32 v59, v246 offset:9104
	ds_read_b32 v60, v246 offset:9376
	ds_read_b32 v61, v246 offset:9648
	ds_read_b32 v62, v246 offset:9920
	ds_read_b32 v63, v246 offset:10192
	ds_read_b32 v64, v246 offset:10464
	ds_read_b32 v65, v246 offset:10736
	ds_read_b32 v74, v244 offset:4224
	ds_read_b32 v75, v244 offset:4356
	ds_read_b32 v76, v244 offset:4488
	ds_read_b32 v77, v244 offset:4620
	s_waitcnt lgkmcnt(15)
	v_mul_f32_e32 v26, v42, v26
	v_mul_f32_e32 v27, v43, v27
	v_mul_f32_e32 v28, v44, v28
	v_mul_f32_e32 v29, v45, v29
	v_mul_f32_e32 v30, v46, v30
	v_mul_f32_e32 v31, v47, v31
	v_mul_f32_e32 v32, v48, v32
	v_mul_f32_e32 v33, v49, v33
	v_mul_f32_e32 v66, v78, v66
	v_mul_f32_e32 v67, v78, v67
	v_mul_f32_e32 v68, v78, v68
	v_mul_f32_e32 v69, v78, v69
	s_nop 1
	v_mfma_f32_16x16x4_f32 v[66:69], v26, v34, v[66:69]
	v_mfma_f32_16x16x4_f32 v[66:69], v27, v35, v[66:69]
	v_mfma_f32_16x16x4_f32 v[66:69], v28, v36, v[66:69]
	v_mfma_f32_16x16x4_f32 v[66:69], v29, v37, v[66:69]
	v_mfma_f32_16x16x4_f32 v[66:69], v30, v38, v[66:69]
	v_mfma_f32_16x16x4_f32 v[66:69], v31, v39, v[66:69]
	v_mfma_f32_16x16x4_f32 v[66:69], v32, v40, v[66:69]
	v_mfma_f32_16x16x4_f32 v[66:69], v33, v41, v[66:69]
	s_waitcnt lgkmcnt(12)
	v_mul_f32_e32 v50, v42, v50
	v_mul_f32_e32 v51, v43, v51
	v_mul_f32_e32 v52, v44, v52
	v_mul_f32_e32 v53, v45, v53
	v_mul_f32_e32 v54, v46, v54
	v_mul_f32_e32 v55, v47, v55
	v_mul_f32_e32 v56, v48, v56
	v_mul_f32_e32 v57, v49, v57
	v_mul_f32_e32 v70, v78, v70
	v_mul_f32_e32 v71, v78, v71
	v_mul_f32_e32 v72, v78, v72
	v_mul_f32_e32 v73, v78, v73
	s_nop 1
	v_mfma_f32_16x16x4_f32 v[70:73], v50, v34, v[70:73]
	v_mfma_f32_16x16x4_f32 v[70:73], v51, v35, v[70:73]
	v_mfma_f32_16x16x4_f32 v[70:73], v52, v36, v[70:73]
	v_mfma_f32_16x16x4_f32 v[70:73], v53, v37, v[70:73]
	v_mfma_f32_16x16x4_f32 v[70:73], v54, v38, v[70:73]
	v_mfma_f32_16x16x4_f32 v[70:73], v55, v39, v[70:73]
	v_mfma_f32_16x16x4_f32 v[70:73], v56, v40, v[70:73]
	v_mfma_f32_16x16x4_f32 v[70:73], v57, v41, v[70:73]
	s_waitcnt lgkmcnt(0)
	v_mul_f32_e32 v58, v42, v58
	v_mul_f32_e32 v59, v43, v59
	v_mul_f32_e32 v60, v44, v60
	v_mul_f32_e32 v61, v45, v61
	v_mul_f32_e32 v62, v46, v62
	v_mul_f32_e32 v63, v47, v63
	v_mul_f32_e32 v64, v48, v64
	v_mul_f32_e32 v65, v49, v65
	v_mul_f32_e32 v74, v78, v74
	v_mul_f32_e32 v75, v78, v75
	v_mul_f32_e32 v76, v78, v76
	v_mul_f32_e32 v77, v78, v77
	s_nop 1
	v_mfma_f32_16x16x4_f32 v[74:77], v58, v34, v[74:77]
	v_mfma_f32_16x16x4_f32 v[74:77], v59, v35, v[74:77]
	v_mfma_f32_16x16x4_f32 v[74:77], v60, v36, v[74:77]
	v_mfma_f32_16x16x4_f32 v[74:77], v61, v37, v[74:77]
	v_mfma_f32_16x16x4_f32 v[74:77], v62, v38, v[74:77]
	v_mfma_f32_16x16x4_f32 v[74:77], v63, v39, v[74:77]
	v_mfma_f32_16x16x4_f32 v[74:77], v64, v40, v[74:77]
	v_mfma_f32_16x16x4_f32 v[74:77], v65, v41, v[74:77]
	s_nop 7
	s_nop 3
	ds_write_b32 v244, v66 offset:0
	ds_write_b32 v244, v67 offset:132
	ds_write_b32 v244, v68 offset:264
	ds_write_b32 v244, v69 offset:396
	ds_write_b32 v244, v70 offset:2112
	ds_write_b32 v244, v71 offset:2244
	ds_write_b32 v244, v72 offset:2376
	ds_write_b32 v244, v73 offset:2508
	ds_write_b32 v244, v74 offset:4224
	ds_write_b32 v244, v75 offset:4356
	ds_write_b32 v244, v76 offset:4488
	ds_write_b32 v244, v77 offset:4620
.Ldc_done:
	s_waitcnt lgkmcnt(0)
	s_branch .LBB0_192
